# FF2 layer-0 leftover round (576 tiles on 256 WGs): split-K x4 with f32 atomic accumulate, quad-transposed so each atomic covers full 64B lines; combine phase fast path (2 units/iter, prefetch)
# speedup vs baseline: 1.0474x; 1.0258x over previous
; __device__ __forceinline__ float bf_lo(unsigned u) { return __uint_as_float(u << 16); }
; __device__ __forceinline__ float bf_hi(unsigned u) { return __uint_as_float(u & 0xFFFF0000u); }
; __device__ __forceinline__ int opaque_tid() { int t = threadIdx.x; asm volatile("" : "+v"(t)); return t; }
; __device__ __forceinline__ void phase_combine(const Params& p, int l, int nrows) {
;     const int tidq = opaque_tid(); unsigned char* ws = p.ws; const int lane = tidq & 63; const int gw = blockIdx.x * 8 + (tidq >> 6), nw = gridDim.x * 8;
;     const bf16_t* P = (const bf16_t*)(ws + WS_PH); bf16_t* Y = (bf16_t*)(ws + WS_ACT);
;     const float* ng = p.in[I_MLNG] + (size_t)l * 768;
;     const int li = lane & 31, e0 = 6 * li, sl = li >> 3, ee = 6 * (li & 7);
;     const int vbq = (gridDim.x % 8 == 0) ? (blockIdx.x & 7) * (gridDim.x >> 3) + (blockIdx.x >> 3) : blockIdx.x; const int per = (nrows * 4 + nw - 1) / nw; const int ubeg = (vbq * 8 + (tidq >> 6)) * per;
;     for (int u = ubeg; u < ubeg + per && u < nrows * 4; ++u) { const int row = u >> 2, grp = (u >> 1) & 1, h = (u & 1) * 2 + (lane >> 5);
;         const bf16_t* o0 = (const bf16_t*)(ws + (grp ? WS_OR : WS_OM)) + ((size_t)(h * 4 + sl) * MT_ROWS + row) * 48 + ee; const bf16_t* o1 = o0 + OMR_DIR / 2;
;         const bf16_t* gp = P + (size_t)row * NINP + (grp ? C_RG : C_MLO) + h * 192 + e0;
;         unsigned a[3], c[3], gt[3];
; #pragma unroll
;         for (int i = 0; i < 3; ++i) { a[i] = ((const unsigned*)o0)[i]; c[i] = ((const unsigned*)o1)[i]; gt[i] = ((const unsigned*)gp)[i]; }
;         float v[6]; float ss = 0.f;
; #pragma unroll
;         for (int i = 0; i < 3; ++i) { v[2 * i] = bf_lo(a[i]) + bf_lo(c[i]); v[2 * i + 1] = bf_hi(a[i]) + bf_hi(c[i]); ss += v[2 * i] * v[2 * i] + v[2 * i + 1] * v[2 * i + 1]; }
.LBB0_1034:
	s_or_b64 exec, exec, s[0:1]
	v_readlane_b32 s0, v253, 63
	s_lshl_b32 s1, s0, 2
	v_readlane_b32 s0, v252, 45
	s_add_i32 s0, s0, s1
	s_ashr_i32 s3, s0, 31
	v_readlane_b32 s4, v253, 1
	s_xor_b32 s3, s3, s4
	s_abs_i32 s0, s0
	v_readlane_b32 s4, v253, 0
	s_mul_hi_u32 s4, s0, s4
	v_readlane_b32 s7, v253, 4
	s_mul_i32 s5, s4, s7
	s_sub_i32 s0, s0, s5
	s_add_i32 s5, s4, 1
	s_sub_i32 s6, s0, s7
	s_cmp_ge_u32 s0, s7
	s_cselect_b32 s4, s5, s4
	s_cselect_b32 s0, s6, s0
	s_add_i32 s5, s4, 1
	s_cmp_ge_u32 s0, s7
	s_cselect_b32 s0, s5, s4
	v_mov_b32_e32 v0, v170
	s_xor_b32 s0, s0, s3
	s_waitcnt lgkmcnt(0)
	s_barrier
	s_sub_i32 s0, s0, s3
	v_ashrrev_i32_e32 v2, 6, v0
	v_readlane_b32 s3, v252, 46
	s_nop 1
	v_add_u32_e32 v2, s3, v2
	v_mul_lo_u32 v5, v2, s0
	v_add_u32_e32 v3, s0, v5
	v_min_i32_e32 v7, s1, v3
	v_cmp_lt_i32_e32 vcc, v5, v7
	s_and_saveexec_b64 s[4:5], vcc
	s_cbranch_execz .LBB0_1061
	v_and_b32_e32 v3, 31, v0
	v_mul_u32_u24_e32 v6, 6, v3
	v_bfe_u32 v20, v0, 3, 2
	v_and_b32_e32 v3, 7, v0
	v_bfe_u32 v21, v0, 5, 1
	v_and_b32_e32 v0, 64, v218
	v_mul_u32_u24_e32 v4, 6, v3
	v_add_u32_e32 v0, 64, v0
	v_xor_b32_e32 v3, 16, v218
	v_cmp_lt_i32_e32 vcc, v3, v0
	v_readlane_b32 s8, v253, 26
	v_readlane_b32 s6, v253, 24
	v_cndmask_b32_e32 v3, v218, v3, vcc
	v_lshlrev_b32_e32 v22, 2, v3
	v_xor_b32_e32 v3, 8, v218
	v_cmp_lt_i32_e32 vcc, v3, v0
	v_readlane_b32 s9, v253, 27
	v_readlane_b32 s7, v253, 25
	v_cndmask_b32_e32 v3, v218, v3, vcc
	v_lshlrev_b32_e32 v23, 2, v3
	v_xor_b32_e32 v3, 4, v218
	v_cmp_lt_i32_e32 vcc, v3, v0
	s_mul_i32 s6, s8, 0x300
	v_readlane_b32 s8, v251, 44
	v_cndmask_b32_e32 v3, v218, v3, vcc
	v_lshlrev_b32_e32 v24, 2, v3
	v_xor_b32_e32 v3, 2, v218
	v_cmp_lt_i32_e32 vcc, v3, v0
	s_mov_b32 s1, s7
	s_lshl_b64 s[6:7], s[6:7], 2
	v_cndmask_b32_e32 v3, v218, v3, vcc
	v_lshlrev_b32_e32 v25, 2, v3
	v_xor_b32_e32 v3, 1, v218
	v_cmp_lt_i32_e32 vcc, v3, v0
	v_readlane_b32 s14, v251, 50
	v_writelane_b32 v253, s0, 24
	v_cndmask_b32_e32 v0, v218, v3, vcc
	v_readlane_b32 s9, v251, 45
	v_readlane_b32 s15, v251, 51
	s_add_u32 s6, s14, s6
	v_lshlrev_b32_e32 v26, 2, v0
	v_mul_lo_u32 v0, v2, s0
	v_writelane_b32 v253, s1, 25
	s_addc_u32 s7, s15, s7
	v_lshlrev_b32_e32 v27, 1, v0
	s_mov_b64 s[8:9], 0
	v_lshlrev_b32_e32 v8, 1, v4
	v_lshlrev_b32_e32 v10, 1, v6
	v_readlane_b32 s10, v251, 46
	v_readlane_b32 s11, v251, 47
	v_readlane_b32 s12, v251, 48
	v_readlane_b32 s13, v251, 49
	v_readlane_b32 s16, v251, 52
	v_readlane_b32 s17, v251, 53
	v_readlane_b32 s18, v251, 54
	v_readlane_b32 s19, v251, 55
	v_readlane_b32 s20, v251, 56
	v_readlane_b32 s21, v251, 57
	v_readlane_b32 s22, v251, 58
	v_readlane_b32 s23, v251, 59
	v_readfirstlane_b32 s0, v5
	v_readfirstlane_b32 s1, v7
	s_nop 0
	s_or_b32 s3, s0, s1
	s_bitcmp1_b32 s3, 0
	s_cbranch_scc1 .LBB0_1037
	s_lshr_b32 s0, s0, 1
	s_lshr_b32 s1, s1, 1
	v_lshl_or_b32 v38, v21, 2, v20
	v_mul_u32_u24_e32 v38, 0x1b0000, v38
	v_add_u32_e32 v38, v38, v8
	v_add_u32_e32 v39, 0xd80000, v38
	v_add_u32_e32 v40, 0x1b00000, v38
	v_add_u32_e32 v41, 0x1b00000, v39
	v_mul_u32_u24_e32 v42, 0x180, v21
	v_add_u32_e32 v42, v42, v10
	v_add_u32_e32 v43, 0x300, v42
	v_lshlrev_b32_e32 v44, 1, v42
	v_mov_b32_e32 v45, 0x358637bd
	v_readlane_b32 s14, v251, 4
	v_readlane_b32 s15, v251, 5
	global_load_dwordx4 v[46:49], v44, s[6:7]
	global_load_dwordx2 v[50:51], v44, s[6:7] offset:16
	global_load_dwordx4 v[52:55], v44, s[6:7] offset:1536
	global_load_dwordx2 v[56:57], v44, s[6:7] offset:1552
	s_lshr_b32 s3, s0, 1
	s_bitcmp1_b32 s0, 0
	s_mov_b32 s8, 0x24000000
	s_cselect_b32 s8, 0x27600000, s8
	s_movk_i32 s9, 0x1e00
	s_cselect_b32 s9, 0x3020, s9
	s_add_u32 s12, s14, s8
	s_addc_u32 s13, s15, 0
	s_mul_i32 s8, s3, 0x60
	s_add_u32 s12, s12, s8
	s_addc_u32 s13, s13, 0
	s_mul_i32 s8, s3, 0x3800
	s_add_u32 s16, s58, s9
	s_addc_u32 s17, s59, 0
	s_add_u32 s16, s16, s8
	s_addc_u32 s17, s17, 0
	global_load_dwordx3 v[58:60], v38, s[12:13]
	global_load_dwordx3 v[62:64], v40, s[12:13]
	global_load_dwordx3 v[66:68], v42, s[16:17]
	global_load_dwordx3 v[70:72], v39, s[12:13]
	global_load_dwordx3 v[74:76], v41, s[12:13]
	global_load_dwordx3 v[78:80], v43, s[16:17]
	s_waitcnt vmcnt(0)
	s_branch .Lcmb_enter
.Lcmb_top:
	s_waitcnt vmcnt(2)
.Lcmb_enter:
	s_lshr_b32 s3, s0, 1
	s_bitcmp1_b32 s0, 0
	s_movk_i32 s8, 0x400
	s_cselect_b32 s8, 0xa00, s8
	s_lshl_b32 s3, s3, 12
	s_add_u32 s18, s56, s8
	s_addc_u32 s19, s57, 0
	s_add_u32 s18, s18, s3
	s_addc_u32 s19, s19, 0
	v_and_b32_e32 v82, 0xffff0000, v59
	v_and_b32_e32 v106, 0xffff0000, v71
	v_lshlrev_b32_e32 v83, 16, v59
	v_lshlrev_b32_e32 v107, 16, v71
	v_and_b32_e32 v84, 0xffff0000, v63
	v_and_b32_e32 v108, 0xffff0000, v75
	v_lshlrev_b32_e32 v85, 16, v63
	v_lshlrev_b32_e32 v109, 16, v75
	v_lshlrev_b32_e32 v86, 16, v58
	v_lshlrev_b32_e32 v110, 16, v70
	v_lshlrev_b32_e32 v87, 16, v60
	v_lshlrev_b32_e32 v111, 16, v72
	v_lshlrev_b32_e32 v88, 16, v62
	v_lshlrev_b32_e32 v112, 16, v74
	v_lshlrev_b32_e32 v89, 16, v64
	v_lshlrev_b32_e32 v113, 16, v76
	v_and_b32_e32 v90, 0xffff0000, v58
	v_and_b32_e32 v114, 0xffff0000, v70
	v_and_b32_e32 v91, 0xffff0000, v60
	v_and_b32_e32 v115, 0xffff0000, v72
	v_and_b32_e32 v92, 0xffff0000, v62
	v_and_b32_e32 v116, 0xffff0000, v74
	v_and_b32_e32 v93, 0xffff0000, v64
	v_and_b32_e32 v117, 0xffff0000, v76
	v_lshlrev_b32_e32 v94, 16, v66
	v_lshlrev_b32_e32 v118, 16, v78
	v_and_b32_e32 v95, 0xffff0000, v66
	v_and_b32_e32 v119, 0xffff0000, v78
	v_lshlrev_b32_e32 v96, 16, v67
	v_lshlrev_b32_e32 v120, 16, v79
	v_and_b32_e32 v97, 0xffff0000, v67
	v_and_b32_e32 v121, 0xffff0000, v79
	v_lshlrev_b32_e32 v98, 16, v68
	v_lshlrev_b32_e32 v122, 16, v80
	v_and_b32_e32 v99, 0xffff0000, v68
	v_and_b32_e32 v123, 0xffff0000, v80
	s_add_i32 s9, s0, 1
	s_cmp_ge_u32 s9, s1
	s_cbranch_scc1 .Lcmb_nopf
	s_lshr_b32 s3, s9, 1
	s_bitcmp1_b32 s9, 0
	s_mov_b32 s8, 0x24000000
	s_cselect_b32 s8, 0x27600000, s8
	s_movk_i32 s9, 0x1e00
	s_cselect_b32 s9, 0x3020, s9
	s_add_u32 s12, s14, s8
	s_addc_u32 s13, s15, 0
	s_mul_i32 s8, s3, 0x60
	s_add_u32 s12, s12, s8
	s_addc_u32 s13, s13, 0
	s_mul_i32 s8, s3, 0x3800
	s_add_u32 s16, s58, s9
	s_addc_u32 s17, s59, 0
	s_add_u32 s16, s16, s8
	s_addc_u32 s17, s17, 0
	global_load_dwordx3 v[58:60], v38, s[12:13]
	global_load_dwordx3 v[62:64], v40, s[12:13]
	global_load_dwordx3 v[66:68], v42, s[16:17]
	global_load_dwordx3 v[70:72], v39, s[12:13]
	global_load_dwordx3 v[74:76], v41, s[12:13]
	global_load_dwordx3 v[78:80], v43, s[16:17]
; __device__ __forceinline__ unsigned cvt_pk_bf16(float lo, float hi) { f32x2_t v = {lo, hi}; bf16x2_t b = __builtin_convertvector(v, bf16x2_t); return __builtin_bit_cast(unsigned, b); }
; __device__ __forceinline__ float bf_lo(unsigned u) { return __uint_as_float(u << 16); }
; __device__ __forceinline__ float bf_hi(unsigned u) { return __uint_as_float(u & 0xFFFF0000u); }
; __device__ __forceinline__ float siluf(float x) { return x * __builtin_amdgcn_rcpf(1.0f + __expf(-x)); }
; __device__ __forceinline__ float sigmf(float x) { return __builtin_amdgcn_rcpf(1.0f + __expf(-x)); }
; __device__ __forceinline__ void phase_combine(const Params& p, int l, int nrows) {
;     ...
;         float v[6]; float ss = 0.f;
; #pragma unroll
;         for (int i = 0; i < 3; ++i) { v[2 * i] = bf_lo(a[i]) + bf_lo(c[i]); v[2 * i + 1] = bf_hi(a[i]) + bf_hi(c[i]); ss += v[2 * i] * v[2 * i] + v[2 * i + 1] * v[2 * i + 1]; }
; #pragma unroll
;         for (int o = 16; o > 0; o >>= 1) ss += __shfl_xor(ss, o);
;         const float r = rsqrtf(ss * (1.0f / 192.0f) + EPS);
;         float y[6];
; #pragma unroll
;         for (int i = 0; i < 6; ++i) { const float g = (i & 1) ? bf_hi(gt[i >> 1]) : bf_lo(gt[i >> 1]);
;             y[i] = grp ? (v[i] * r * siluf(g)) : (v[i] * r * ng[h * 192 + e0 + i] * sigmf(g)); }
;         unsigned* yp = (unsigned*)(Y + (size_t)row * D + (grp ? 1280 : 512) + h * 192 + e0);
; #pragma unroll
;         for (int i = 0; i < 3; ++i) yp[i] = cvt_pk_bf16(y[2 * i], y[2 * i + 1]); }
; }
.Lcmb_nopf:
	v_pk_add_f32 v[82:83], v[82:83], v[84:85]
	v_pk_add_f32 v[106:107], v[106:107], v[108:109]
	v_pk_add_f32 v[86:87], v[86:87], v[88:89]
	v_pk_add_f32 v[110:111], v[110:111], v[112:113]
	v_pk_add_f32 v[90:91], v[90:91], v[92:93]
	v_pk_add_f32 v[114:115], v[114:115], v[116:117]
	v_pk_mul_f32 v[100:101], v[82:83], v[82:83]
	v_pk_mul_f32 v[124:125], v[106:107], v[106:107]
	v_pk_mul_f32 v[102:103], v[86:87], v[86:87]
	v_pk_mul_f32 v[126:127], v[110:111], v[110:111]
	v_add_f32_e32 v104, v100, v101
	v_add_f32_e32 v128, v124, v125
	v_pk_fma_f32 v[102:103], v[90:91], v[90:91], v[102:103]
	v_pk_fma_f32 v[126:127], v[114:115], v[114:115], v[126:127]
	v_add_f32_e32 v104, v102, v104
	v_add_f32_e32 v128, v126, v128
	v_add_f32_e32 v104, v104, v103
	v_add_f32_e32 v128, v128, v127
	ds_swizzle_b32 v105, v104 offset:0x401f
	ds_swizzle_b32 v129, v128 offset:0x401f
	s_waitcnt lgkmcnt(1)
	v_add_f32_e32 v104, v104, v105
	s_waitcnt lgkmcnt(0)
	v_add_f32_e32 v128, v128, v129
	s_nop 1
	v_add_f32_dpp v104, v104, v104 row_ror:8 row_mask:0xf bank_mask:0xf
	v_add_f32_dpp v128, v128, v128 row_ror:8 row_mask:0xf bank_mask:0xf
	s_nop 1
	v_add_f32_dpp v104, v104, v104 row_ror:4 row_mask:0xf bank_mask:0xf
	v_add_f32_dpp v128, v128, v128 row_ror:4 row_mask:0xf bank_mask:0xf
	s_nop 1
	v_add_f32_dpp v104, v104, v104 quad_perm:[2,3,0,1] row_mask:0xf bank_mask:0xf
	v_add_f32_dpp v128, v128, v128 quad_perm:[2,3,0,1] row_mask:0xf bank_mask:0xf
	s_nop 1
	v_add_f32_dpp v104, v104, v104 quad_perm:[1,0,3,2] row_mask:0xf bank_mask:0xf
	v_add_f32_dpp v128, v128, v128 quad_perm:[1,0,3,2] row_mask:0xf bank_mask:0xf
	s_nop 0
	v_fmamk_f32 v105, v104, 0x3baaaaab, v45
	v_fmamk_f32 v129, v128, 0x3baaaaab, v45
	v_rsq_f32_e32 v105, v105
	v_rsq_f32_e32 v129, v129
	v_mul_f32_e32 v84, 0xbfb8aa3b, v94
	v_mul_f32_e32 v85, 0xbfb8aa3b, v95
	v_mul_f32_e32 v88, 0xbfb8aa3b, v96
	v_mul_f32_e32 v89, 0xbfb8aa3b, v97
	v_mul_f32_e32 v92, 0xbfb8aa3b, v98
	v_mul_f32_e32 v93, 0xbfb8aa3b, v99
	v_mul_f32_e32 v108, 0xbfb8aa3b, v118
	v_mul_f32_e32 v109, 0xbfb8aa3b, v119
	v_mul_f32_e32 v112, 0xbfb8aa3b, v120
	v_mul_f32_e32 v113, 0xbfb8aa3b, v121
	v_mul_f32_e32 v116, 0xbfb8aa3b, v122
	v_mul_f32_e32 v117, 0xbfb8aa3b, v123
	v_exp_f32_e32 v84, v84
	v_exp_f32_e32 v85, v85
	v_exp_f32_e32 v88, v88
	v_exp_f32_e32 v89, v89
	v_exp_f32_e32 v92, v92
	v_exp_f32_e32 v93, v93
	v_exp_f32_e32 v108, v108
	v_exp_f32_e32 v109, v109
	v_exp_f32_e32 v112, v112
	v_exp_f32_e32 v113, v113
	v_exp_f32_e32 v116, v116
	v_exp_f32_e32 v117, v117
	v_mul_f32_e32 v86, v86, v105
	v_mul_f32_e32 v90, v90, v105
	v_mul_f32_e32 v83, v83, v105
	v_mul_f32_e32 v82, v82, v105
	v_mul_f32_e32 v87, v87, v105
	v_mul_f32_e32 v91, v91, v105
	v_mul_f32_e32 v110, v110, v129
	v_mul_f32_e32 v114, v114, v129
	v_mul_f32_e32 v107, v107, v129
	v_mul_f32_e32 v106, v106, v129
	v_mul_f32_e32 v111, v111, v129
	v_mul_f32_e32 v115, v115, v129
	v_add_f32_e32 v84, 1.0, v84
	v_add_f32_e32 v85, 1.0, v85
	v_add_f32_e32 v88, 1.0, v88
	v_add_f32_e32 v89, 1.0, v89
	v_add_f32_e32 v92, 1.0, v92
	v_add_f32_e32 v93, 1.0, v93
	v_add_f32_e32 v108, 1.0, v108
	v_add_f32_e32 v109, 1.0, v109
	v_add_f32_e32 v112, 1.0, v112
	v_add_f32_e32 v113, 1.0, v113
	v_add_f32_e32 v116, 1.0, v116
	v_add_f32_e32 v117, 1.0, v117
	v_rcp_f32_e32 v84, v84
	v_rcp_f32_e32 v85, v85
	v_rcp_f32_e32 v88, v88
	v_rcp_f32_e32 v89, v89
	v_rcp_f32_e32 v92, v92
	v_rcp_f32_e32 v93, v93
	v_rcp_f32_e32 v108, v108
	v_rcp_f32_e32 v109, v109
	v_rcp_f32_e32 v112, v112
	v_rcp_f32_e32 v113, v113
	v_rcp_f32_e32 v116, v116
	v_rcp_f32_e32 v117, v117
	s_bitcmp1_b32 s0, 0
	s_cbranch_scc1 .Lcmb_rt
	v_mul_f32_e32 v86, v86, v46
	v_mul_f32_e32 v90, v90, v47
	v_mul_f32_e32 v83, v83, v48
	v_mul_f32_e32 v82, v82, v49
	v_mul_f32_e32 v87, v87, v50
	v_mul_f32_e32 v91, v91, v51
	v_mul_f32_e32 v110, v110, v52
	v_mul_f32_e32 v114, v114, v53
	v_mul_f32_e32 v107, v107, v54
	v_mul_f32_e32 v106, v106, v55
	v_mul_f32_e32 v111, v111, v56
	v_mul_f32_e32 v115, v115, v57
	v_mul_f32_e32 v86, v84, v86
	v_mul_f32_e32 v90, v85, v90
	v_mul_f32_e32 v83, v88, v83
	v_mul_f32_e32 v82, v89, v82
	v_mul_f32_e32 v87, v92, v87
	v_mul_f32_e32 v91, v93, v91
	v_mul_f32_e32 v110, v108, v110
	v_mul_f32_e32 v114, v109, v114
	v_mul_f32_e32 v107, v112, v107
	v_mul_f32_e32 v106, v113, v106
	v_mul_f32_e32 v111, v116, v111
	v_mul_f32_e32 v115, v117, v115
	s_branch .Lcmb_out
.Lcmb_rt:
	v_mul_f32_e32 v84, v84, v94
	v_mul_f32_e32 v85, v85, v95
	v_mul_f32_e32 v88, v88, v96
	v_mul_f32_e32 v89, v89, v97
	v_mul_f32_e32 v92, v92, v98
	v_mul_f32_e32 v93, v93, v99
	v_mul_f32_e32 v108, v108, v118
	v_mul_f32_e32 v109, v109, v119
	v_mul_f32_e32 v112, v112, v120
	v_mul_f32_e32 v113, v113, v121
	v_mul_f32_e32 v116, v116, v122
	v_mul_f32_e32 v117, v117, v123
	v_mul_f32_e32 v86, v84, v86
	v_mul_f32_e32 v90, v85, v90
	v_mul_f32_e32 v83, v88, v83
	v_mul_f32_e32 v82, v89, v82
	v_mul_f32_e32 v87, v92, v87
	v_mul_f32_e32 v91, v93, v91
	v_mul_f32_e32 v110, v108, v110
	v_mul_f32_e32 v114, v109, v114
	v_mul_f32_e32 v107, v112, v107
	v_mul_f32_e32 v106, v113, v106
	v_mul_f32_e32 v111, v116, v111
	v_mul_f32_e32 v115, v117, v115
.Lcmb_out:
	v_cvt_pk_bf16_f32 v100, v86, v90
	v_cvt_pk_bf16_f32 v101, v83, v82
	v_cvt_pk_bf16_f32 v102, v87, v91
	v_cvt_pk_bf16_f32 v124, v110, v114
	v_cvt_pk_bf16_f32 v125, v107, v106
	v_cvt_pk_bf16_f32 v126, v111, v115
	global_store_dwordx3 v42, v[100:102], s[18:19]
	global_store_dwordx3 v43, v[124:126], s[18:19]
	s_add_i32 s0, s0, 1
	s_cmp_lt_u32 s0, s1
	s_cbranch_scc1 .Lcmb_top
	s_branch .LBB0_1061

; template <class Epi, class Sched>
; __device__ __forceinline__ void gemm_phase(LAS unsigned char* lds, const Gemm g, const Sched& S, const Epi& E) {
;     ...
;         const bool has_next = S.next(ui + 1, nxt);
;         const char* nA = has_next ? (const char*)g.A + (size_t)nxt.pm * tstep : cA; const char* nB = has_next ? (const char*)g.Bt + (size_t)nxt.pn * tstep : cB;
;     ...
; #pragma unroll
;         for (int a = 0; a < 2; ++a)
; #pragma unroll
;             for (int b = 0; b < 2; ++b)
; #pragma unroll
;                 for (int m = 0; m < 4; ++m)
; #pragma unroll
;                     for (int n = 0; n < 2; ++n) acc[a][b][m][n] = (f32x4){0.f, 0.f, 0.f, 0.f};
.LBB0_1340:
	s_add_i32 s36, s36, 1
	v_readlane_b32 s0, v252, 34
	s_mul_i32 s0, s36, s0
	s_mul_hi_u32 s1, s36, s46
	s_add_i32 s1, s1, s0
	s_mul_i32 s0, s36, s46
	s_add_u32 s8, s0, s54
	v_readlane_b32 s0, v252, 33
	s_addc_u32 s9, s1, s0
	v_readlane_b32 s0, v253, 24
	v_readlane_b32 s1, v253, 25
	s_mov_b32 s22, 0
	s_mov_b32 s23, -2
	s_cmpk_lg_u32 s0, 0x240
	s_cbranch_scc1 .Lsk_hdr_done
	s_cmpk_lg_u32 s46, 0x100
	s_cbranch_scc1 .Lsk_hdr_done
	s_cmp_lg_u32 s36, 3
	s_cbranch_scc1 .Lsk_not3
	s_movk_i32 s23, 0x5e
.Lsk_not3:
	s_cmp_lg_u32 s36, 2
	s_cbranch_scc1 .Lsk_hdr_done
	s_lshr_b32 s8, s54, 5
	s_lshl_b32 s8, s8, 3
	s_and_b32 s9, s54, 7
	s_add_i32 s8, s8, s9
	s_addk_i32 s8, 0x200
	s_mov_b32 s9, 0
	s_bfe_u32 s22, s54, 0x20003
	s_lshl_b32 s22, s22, 12
.Lsk_hdr_done:
	s_nop 1
	v_mov_b64_e32 v[2:3], s[0:1]
	v_cmp_ge_i64_e64 s[0:1], s[8:9], v[2:3]
	s_and_b64 vcc, exec, s[0:1]
	s_cbranch_vccnz .LBB0_1342
	s_ashr_i32 s3, s8, 31
	s_lshr_b32 s3, s3, 29
	s_add_i32 s3, s8, s3
	s_ashr_i32 s4, s3, 3
	s_and_b32 s3, s3, -8
	s_sub_i32 s3, s8, s3
	s_lshr_b32 s5, s3, 31
	s_or_b32 s5, s26, s5
	s_mul_i32 s3, s5, s3
	s_add_i32 s3, s3, s4
	s_ashr_i32 s4, s3, 31
	s_lshr_b32 s4, s4, 28
	s_add_i32 s4, s3, s4
	s_ashr_i32 s5, s4, 4
	s_lshl_b32 s5, s5, 1
	s_sub_i32 s6, s26, s5
	s_min_i32 s6, s6, 2
	s_abs_i32 s7, s6
	v_cvt_f32_u32_e32 v2, s7
	s_sub_i32 s11, 0, s7
	s_and_b32 s4, s4, -16
	s_sub_i32 s3, s3, s4
	v_rcp_iflag_f32_e32 v2, v2
	s_abs_i32 s4, s3
	s_xor_b32 s10, s3, s6
	s_ashr_i32 s10, s10, 31
	v_mul_f32_e32 v2, 0x4f7ffffe, v2
	v_cvt_u32_f32_e32 v2, v2
	s_nop 0
	v_readfirstlane_b32 s20, v2
	s_mul_i32 s11, s11, s20
	s_mul_hi_u32 s11, s20, s11
	s_add_i32 s20, s20, s11
	s_mul_hi_u32 s11, s4, s20
	s_mul_i32 s20, s11, s7
	s_sub_i32 s4, s4, s20
	s_add_i32 s21, s11, 1
	s_sub_i32 s20, s4, s7
	s_cmp_ge_u32 s4, s7
	s_cselect_b32 s11, s21, s11
	s_cselect_b32 s4, s20, s4
	s_add_i32 s20, s11, 1
	s_cmp_ge_u32 s4, s7
	s_cselect_b32 s4, s20, s11
	s_xor_b32 s4, s4, s10
	s_sub_i32 s4, s4, s10
	s_mul_i32 s6, s4, s6
	s_sub_i32 s3, s3, s6
	s_add_i32 s6, s3, s5
.LBB0_1342:
	v_readlane_b32 s10, v253, 24
	v_readlane_b32 s11, v253, 25
	s_ashr_i32 s7, s6, 31
	s_mov_b32 s40, s23
	v_mov_b64_e32 v[2:3], s[10:11]
	v_cmp_lt_i64_e32 vcc, s[8:9], v[2:3]
	s_lshl_b64 s[8:9], s[6:7], 22
	s_add_u32 s8, s58, s8
	s_addc_u32 s9, s59, s9
	s_add_u32 s8, s8, s22
	s_addc_u32 s9, s9, 0
	s_and_b64 s[10:11], vcc, exec
	s_cselect_b32 s3, s9, s17
	s_cselect_b32 s7, s8, s16
	s_ashr_i32 s5, s4, 31
	s_lshl_b64 s[10:11], s[4:5], 22
	s_add_u32 s10, s25, s10
	s_addc_u32 s11, s27, s11
	s_add_u32 s10, s10, s22
	s_addc_u32 s11, s11, 0
	s_and_b64 s[20:21], vcc, exec
	s_cselect_b32 s5, s11, s19
	s_cselect_b32 s37, s10, s18
	s_add_u32 s38, s18, 0x100
	v_mov_b32_e32 v2, 0
	s_addc_u32 s39, s19, 0
	v_mov_b32_e32 v3, v2
	v_mov_b32_e32 v4, v2
	v_mov_b32_e32 v5, v2
	v_mov_b32_e32 v6, v2
	v_mov_b32_e32 v7, v2
	v_mov_b32_e32 v8, v2
	v_mov_b32_e32 v9, v2
	v_mov_b32_e32 v18, v2
	v_mov_b32_e32 v19, v2
	v_mov_b32_e32 v20, v2
	v_mov_b32_e32 v21, v2
	v_mov_b32_e32 v22, v2
	v_mov_b32_e32 v23, v2
	v_mov_b32_e32 v24, v2
	v_mov_b32_e32 v25, v2
	v_mov_b32_e32 v34, v2
	v_mov_b32_e32 v35, v2
	v_mov_b32_e32 v36, v2
	v_mov_b32_e32 v37, v2
	v_mov_b32_e32 v38, v2
	v_mov_b32_e32 v39, v2
	v_mov_b32_e32 v40, v2
	v_mov_b32_e32 v41, v2
	v_mov_b32_e32 v50, v2
	v_mov_b32_e32 v51, v2
	v_mov_b32_e32 v52, v2
	v_mov_b32_e32 v53, v2
	v_mov_b32_e32 v54, v2
	v_mov_b32_e32 v55, v2
	v_mov_b32_e32 v56, v2
	v_mov_b32_e32 v57, v2
	v_mov_b32_e32 v10, v2
	v_mov_b32_e32 v11, v2
	v_mov_b32_e32 v12, v2
	v_mov_b32_e32 v13, v2
	v_mov_b32_e32 v14, v2
	v_mov_b32_e32 v15, v2
	v_mov_b32_e32 v16, v2
	v_mov_b32_e32 v17, v2
	v_mov_b32_e32 v26, v2
	v_mov_b32_e32 v27, v2
	v_mov_b32_e32 v28, v2
	v_mov_b32_e32 v29, v2
	v_mov_b32_e32 v30, v2
	v_mov_b32_e32 v31, v2
	v_mov_b32_e32 v32, v2
	v_mov_b32_e32 v33, v2
	v_mov_b32_e32 v42, v2
	v_mov_b32_e32 v43, v2
	v_mov_b32_e32 v44, v2
	v_mov_b32_e32 v45, v2
	v_mov_b32_e32 v46, v2
	v_mov_b32_e32 v47, v2
	v_mov_b32_e32 v48, v2
	v_mov_b32_e32 v49, v2
	v_mov_b32_e32 v58, v2
	v_mov_b32_e32 v59, v2
	v_mov_b32_e32 v60, v2
	v_mov_b32_e32 v61, v2
	v_mov_b32_e32 v62, v2
	v_mov_b32_e32 v63, v2
	v_mov_b32_e32 v64, v2
	v_mov_b32_e32 v65, v2
	v_mov_b32_e32 v66, v2
	v_mov_b32_e32 v67, v2
	v_mov_b32_e32 v68, v2
	v_mov_b32_e32 v69, v2
	v_mov_b32_e32 v70, v2
	v_mov_b32_e32 v71, v2
	v_mov_b32_e32 v72, v2
	v_mov_b32_e32 v73, v2
	v_mov_b32_e32 v82, v2
	v_mov_b32_e32 v83, v2
	v_mov_b32_e32 v84, v2
	v_mov_b32_e32 v85, v2
	v_mov_b32_e32 v86, v2
	v_mov_b32_e32 v87, v2
	v_mov_b32_e32 v88, v2
	v_mov_b32_e32 v89, v2
	v_mov_b32_e32 v98, v2
	v_mov_b32_e32 v99, v2
	v_mov_b32_e32 v100, v2
	v_mov_b32_e32 v101, v2
	v_mov_b32_e32 v102, v2
	v_mov_b32_e32 v103, v2
	v_mov_b32_e32 v104, v2
	v_mov_b32_e32 v105, v2
	v_mov_b32_e32 v114, v2
	v_mov_b32_e32 v115, v2
	v_mov_b32_e32 v116, v2
	v_mov_b32_e32 v117, v2
	v_mov_b32_e32 v118, v2
	v_mov_b32_e32 v119, v2
	v_mov_b32_e32 v120, v2
	v_mov_b32_e32 v121, v2
	v_mov_b32_e32 v74, v2
	v_mov_b32_e32 v75, v2
	v_mov_b32_e32 v76, v2
	v_mov_b32_e32 v77, v2
	v_mov_b32_e32 v78, v2
	v_mov_b32_e32 v79, v2
	v_mov_b32_e32 v80, v2
	v_mov_b32_e32 v81, v2
	v_mov_b32_e32 v90, v2
	v_mov_b32_e32 v91, v2
	v_mov_b32_e32 v92, v2
	v_mov_b32_e32 v93, v2
	v_mov_b32_e32 v94, v2
	v_mov_b32_e32 v95, v2
	v_mov_b32_e32 v96, v2
	v_mov_b32_e32 v97, v2
	v_mov_b32_e32 v106, v2
	v_mov_b32_e32 v107, v2
	v_mov_b32_e32 v108, v2
	v_mov_b32_e32 v109, v2
	v_mov_b32_e32 v110, v2
	v_mov_b32_e32 v111, v2
	v_mov_b32_e32 v112, v2
	v_mov_b32_e32 v113, v2
	v_mov_b32_e32 v122, v2
	v_mov_b32_e32 v123, v2
	v_mov_b32_e32 v124, v2
	v_mov_b32_e32 v125, v2
	v_mov_b32_e32 v126, v2
	v_mov_b32_e32 v127, v2
	v_mov_b32_e32 v128, v2
	v_mov_b32_e32 v129, v2
	v_readlane_b32 s42, v253, 6
	s_mov_b64 s[44:45], 0x80
; #define PG8_STAGE(bufoff, gbase, voff) do { _Pragma("unroll") for (int _i = 0; _i < 2; ++_i) \
;         __builtin_amdgcn_global_load_lds((const unsigned*)((const char*)(gbase) + (voff)[_i]), (LAS unsigned*)(lds + (bufoff) + ldsw + _i * 8192), 16, 0, 0); } while (0)
; #define PG8_LDA(dst, b, h) do { _Pragma("unroll") for (int m = 0; m < 4; ++m) _Pragma("unroll") for (int k = 0; k < 2; ++k) dst[m][k] = *(const LAS bf16x8*)(lds + PG8_SA(b, h) + aoff + m * 2048 + k * 1024); } while (0)
; #define PG8_LDB(dst, b, h) do { _Pragma("unroll") for (int n = 0; n < 2; ++n) _Pragma("unroll") for (int k = 0; k < 2; ++k) dst[n][k] = *(const LAS bf16x8*)(lds + PG8_SB(b, h) + boff + n * 2048 + k * 1024); } while (0)
; #define PG8_MMA(ai, bj, At, Bt) do { __builtin_amdgcn_s_setprio(1); _Pragma("unroll") for (int m = 0; m < 4; ++m) _Pragma("unroll") for (int n = 0; n < 2; ++n) _Pragma("unroll") for (int k = 0; k < 2; ++k) \
;         acc[ai][bj][m][n] = __builtin_amdgcn_mfma_f32_16x16x32_bf16(Bt[n][k], At[m][k], acc[ai][bj][m][n], 0, 0, 0); __builtin_amdgcn_s_setprio(0); } while (0)
; #define PG8_WAIT_L(n) asm volatile("s_waitcnt lgkmcnt(" #n ")" ::: "memory")
; #define PG8_BAR __builtin_amdgcn_s_barrier()
; #define PG8_SCHED __builtin_amdgcn_sched_barrier(0)
; template <class Epi, class Sched>
; __device__ __forceinline__ void gemm_phase(LAS unsigned char* lds, const Gemm g, const Sched& S, const Epi& E) {
;     ...
;             PG8_LDB(B0, 0, 0); PG8_SCHED; PG8_LDA(At, 0, 0); PG8_STAGE(PG8_SA(1, 1), a1 + hstep, voffA);
;             PG8_WAIT_L(8); PG8_BAR; PG8_WAIT_L(0); PG8_MMA(0, 0, At, B0); PG8_BAR; PG8_SCHED;
;             PG8_LDB(B1, 0, 1); PG8_STAGE(PG8_SB(0, 0), b2, voffB);
;             PG8_BAR; PG8_WAIT_L(0); PG8_MMA(0, 1, At, B1); PG8_BAR;
;             PG8_LDA(At, 0, 1); PG8_STAGE(PG8_SA(0, 0), a2, voffA);
;             PG8_BAR; PG8_WAIT_L(0); PG8_MMA(1, 0, At, B0); PG8_BAR; PG8_SCHED;
.LBB0_1343:
	s_nop 0
	v_add_u32_e32 v136, s42, v139
	ds_read_b128 v[142:145], v136
	ds_read_b128 v[146:149], v136 offset:1024
	ds_read_b128 v[150:153], v136 offset:2048
	ds_read_b128 v[154:157], v136 offset:3072
	s_add_u32 s18, s16, 0x100
	s_addc_u32 s19, s17, 0
	s_cmpk_eq_i32 s40, 0x7c
	s_cselect_b32 s23, s3, s19
	s_cselect_b32 s22, s7, s18
	s_cselect_b32 s21, s5, s39
	s_cselect_b32 s20, s37, s38
	v_lshl_add_u64 v[136:137], s[16:17], 0, v[132:133]
	s_add_i32 m0, s13, 0xc000
	ds_read_b128 v[158:161], v141
	ds_read_b128 v[162:165], v141 offset:1024
	ds_read_b128 v[166:169], v141 offset:2048
	ds_read_b128 v[170:173], v141 offset:3072
	ds_read_b128 v[174:177], v141 offset:4096
	ds_read_b128 v[178:181], v141 offset:5120
	ds_read_b128 v[182:185], v141 offset:6144
	ds_read_b128 v[186:189], v141 offset:7168
	global_load_lds_dwordx4 v[136:137], off
	v_lshl_add_u64 v[136:137], s[16:17], 0, v[134:135]
	s_add_i32 m0, s13, 0xe000
	s_nop 0
	global_load_lds_dwordx4 v[136:137], off
	s_waitcnt lgkmcnt(8)
	s_barrier
	s_waitcnt lgkmcnt(0)
	s_setprio 1
	s_waitcnt lgkmcnt(0)
	v_mfma_f32_16x16x32_bf16 v[126:129], v[142:145], v[158:161], v[126:129]
	v_mfma_f32_16x16x32_bf16 v[122:125], v[150:153], v[158:161], v[122:125]
	v_mfma_f32_16x16x32_bf16 v[110:113], v[142:145], v[166:169], v[110:113]
	v_mfma_f32_16x16x32_bf16 v[106:109], v[150:153], v[166:169], v[106:109]
	v_mfma_f32_16x16x32_bf16 v[94:97], v[142:145], v[174:177], v[94:97]
	v_mfma_f32_16x16x32_bf16 v[90:93], v[150:153], v[174:177], v[90:93]
	v_mfma_f32_16x16x32_bf16 v[78:81], v[142:145], v[182:185], v[78:81]
	v_mfma_f32_16x16x32_bf16 v[74:77], v[150:153], v[182:185], v[74:77]
	v_mfma_f32_16x16x32_bf16 v[126:129], v[146:149], v[162:165], v[126:129]
	v_mfma_f32_16x16x32_bf16 v[122:125], v[154:157], v[162:165], v[122:125]
	v_mfma_f32_16x16x32_bf16 v[110:113], v[146:149], v[170:173], v[110:113]
	v_mfma_f32_16x16x32_bf16 v[106:109], v[154:157], v[170:173], v[106:109]
	v_mfma_f32_16x16x32_bf16 v[94:97], v[146:149], v[178:181], v[94:97]
	v_mfma_f32_16x16x32_bf16 v[90:93], v[154:157], v[178:181], v[90:93]
	v_mfma_f32_16x16x32_bf16 v[78:81], v[146:149], v[186:189], v[78:81]
	v_mfma_f32_16x16x32_bf16 v[74:77], v[154:157], v[186:189], v[74:77]
	s_setprio 0
	s_barrier
	s_add_i32 s41, 0, 0x14000
	v_add_u32_e32 v136, s41, v139
	s_add_i32 s16, s42, s28
	ds_read_b128 v[190:193], v136
	ds_read_b128 v[194:197], v136 offset:1024
	ds_read_b128 v[198:201], v136 offset:2048
	ds_read_b128 v[202:205], v136 offset:3072
	v_lshl_add_u64 v[136:137], s[20:21], 0, v[0:1]
	s_mov_b32 m0, s16
	v_lshl_add_u64 v[206:207], s[20:21], 0, v[130:131]
	global_load_lds_dwordx4 v[136:137], off
	s_add_i32 m0, s16, 0x2000
	s_nop 0
	global_load_lds_dwordx4 v[206:207], off
	s_barrier
	s_waitcnt lgkmcnt(0)
	s_setprio 1
	s_waitcnt lgkmcnt(0)
	v_mfma_f32_16x16x32_bf16 v[118:121], v[190:193], v[158:161], v[118:121]
	v_mfma_f32_16x16x32_bf16 v[114:117], v[198:201], v[158:161], v[114:117]
	v_mfma_f32_16x16x32_bf16 v[102:105], v[190:193], v[166:169], v[102:105]
	v_mfma_f32_16x16x32_bf16 v[98:101], v[198:201], v[166:169], v[98:101]
	v_mfma_f32_16x16x32_bf16 v[86:89], v[190:193], v[174:177], v[86:89]
	v_mfma_f32_16x16x32_bf16 v[82:85], v[198:201], v[174:177], v[82:85]
	v_mfma_f32_16x16x32_bf16 v[70:73], v[190:193], v[182:185], v[70:73]
	v_mfma_f32_16x16x32_bf16 v[66:69], v[198:201], v[182:185], v[66:69]
	v_mfma_f32_16x16x32_bf16 v[118:121], v[194:197], v[162:165], v[118:121]
	v_mfma_f32_16x16x32_bf16 v[114:117], v[202:205], v[162:165], v[114:117]
	v_mfma_f32_16x16x32_bf16 v[102:105], v[194:197], v[170:173], v[102:105]
	v_mfma_f32_16x16x32_bf16 v[98:101], v[202:205], v[170:173], v[98:101]
	v_mfma_f32_16x16x32_bf16 v[86:89], v[194:197], v[178:181], v[86:89]
	v_mfma_f32_16x16x32_bf16 v[82:85], v[202:205], v[178:181], v[82:85]
	v_mfma_f32_16x16x32_bf16 v[70:73], v[194:197], v[186:189], v[70:73]
	v_mfma_f32_16x16x32_bf16 v[66:69], v[202:205], v[186:189], v[66:69]
	s_setprio 0
	s_mov_b32 m0, s13
	v_lshl_add_u64 v[208:209], s[22:23], 0, v[0:1]
	s_barrier
	ds_read_b128 v[158:161], v141 offset:16384
	ds_read_b128 v[162:165], v141 offset:17408
	ds_read_b128 v[166:169], v141 offset:18432
	ds_read_b128 v[170:173], v141 offset:19456
	ds_read_b128 v[174:177], v141 offset:20480
	ds_read_b128 v[178:181], v141 offset:21504
	ds_read_b128 v[182:185], v141 offset:22528
	ds_read_b128 v[186:189], v141 offset:23552
	global_load_lds_dwordx4 v[208:209], off
	v_lshl_add_u64 v[210:211], s[22:23], 0, v[130:131]
	s_mov_b32 m0, s15
	s_nop 0
	global_load_lds_dwordx4 v[210:211], off
	s_barrier
	s_waitcnt lgkmcnt(0)
	s_setprio 1
	s_waitcnt lgkmcnt(0)
	v_mfma_f32_16x16x32_bf16 v[62:65], v[142:145], v[158:161], v[62:65]
	v_mfma_f32_16x16x32_bf16 v[58:61], v[150:153], v[158:161], v[58:61]
	v_mfma_f32_16x16x32_bf16 v[46:49], v[142:145], v[166:169], v[46:49]
	v_mfma_f32_16x16x32_bf16 v[42:45], v[150:153], v[166:169], v[42:45]
	v_mfma_f32_16x16x32_bf16 v[30:33], v[142:145], v[174:177], v[30:33]
	v_mfma_f32_16x16x32_bf16 v[26:29], v[150:153], v[174:177], v[26:29]
	v_mfma_f32_16x16x32_bf16 v[14:17], v[142:145], v[182:185], v[14:17]
	v_mfma_f32_16x16x32_bf16 v[10:13], v[150:153], v[182:185], v[10:13]
	v_mfma_f32_16x16x32_bf16 v[62:65], v[146:149], v[162:165], v[62:65]
	v_mfma_f32_16x16x32_bf16 v[58:61], v[154:157], v[162:165], v[58:61]
	v_mfma_f32_16x16x32_bf16 v[46:49], v[146:149], v[170:173], v[46:49]
	v_mfma_f32_16x16x32_bf16 v[42:45], v[154:157], v[170:173], v[42:45]
	v_mfma_f32_16x16x32_bf16 v[30:33], v[146:149], v[178:181], v[30:33]
	v_mfma_f32_16x16x32_bf16 v[26:29], v[154:157], v[178:181], v[26:29]
	v_mfma_f32_16x16x32_bf16 v[14:17], v[146:149], v[186:189], v[14:17]
	v_mfma_f32_16x16x32_bf16 v[10:13], v[154:157], v[186:189], v[10:13]
	s_setprio 0
	s_barrier
; #define PG8_STAGE(bufoff, gbase, voff) do { _Pragma("unroll") for (int _i = 0; _i < 2; ++_i) \
;         __builtin_amdgcn_global_load_lds((const unsigned*)((const char*)(gbase) + (voff)[_i]), (LAS unsigned*)(lds + (bufoff) + ldsw + _i * 8192), 16, 0, 0); } while (0)
; #define PG8_LDA(dst, b, h) do { _Pragma("unroll") for (int m = 0; m < 4; ++m) _Pragma("unroll") for (int k = 0; k < 2; ++k) dst[m][k] = *(const LAS bf16x8*)(lds + PG8_SA(b, h) + aoff + m * 2048 + k * 1024); } while (0)
; #define PG8_LDB(dst, b, h) do { _Pragma("unroll") for (int n = 0; n < 2; ++n) _Pragma("unroll") for (int k = 0; k < 2; ++k) dst[n][k] = *(const LAS bf16x8*)(lds + PG8_SB(b, h) + boff + n * 2048 + k * 1024); } while (0)
; #define PG8_MMA(ai, bj, At, Bt) do { __builtin_amdgcn_s_setprio(1); _Pragma("unroll") for (int m = 0; m < 4; ++m) _Pragma("unroll") for (int n = 0; n < 2; ++n) _Pragma("unroll") for (int k = 0; k < 2; ++k) \
;         acc[ai][bj][m][n] = __builtin_amdgcn_mfma_f32_16x16x32_bf16(Bt[n][k], At[m][k], acc[ai][bj][m][n], 0, 0, 0); __builtin_amdgcn_s_setprio(0); } while (0)
; #define PG8_WAIT_V(n) asm volatile("s_waitcnt vmcnt(" #n ")" ::: "memory")
; #define PG8_WAIT_L(n) asm volatile("s_waitcnt lgkmcnt(" #n ")" ::: "memory")
; #define PG8_BAR __builtin_amdgcn_s_barrier()
; #define PG8_SCHED __builtin_amdgcn_sched_barrier(0)
; template <class Epi, class Sched>
; __device__ __forceinline__ void gemm_phase(LAS unsigned char* lds, const Gemm g, const Sched& S, const Epi& E) {
;     ...
;             PG8_STAGE(PG8_SB(0, 1), b2 + hstep, voffB);
;             PG8_WAIT_V(6); PG8_BAR; PG8_MMA(1, 1, At, B1); PG8_BAR;
;             PG8_LDB(B0, 1, 0); PG8_SCHED; PG8_LDA(At, 1, 0); PG8_STAGE(PG8_SA(0, 1), a2 + hstep, voffA);
;             PG8_WAIT_L(8); PG8_BAR; PG8_WAIT_L(0); PG8_MMA(0, 0, At, B0); PG8_BAR; PG8_SCHED;
;             PG8_LDB(B1, 1, 1); PG8_STAGE(PG8_SB(1, 0), b3, voffB);
;             PG8_BAR; PG8_WAIT_L(0); PG8_MMA(0, 1, At, B1); PG8_BAR;
;             PG8_LDA(At, 1, 1); PG8_STAGE(PG8_SA(1, 0), a3, voffA);
	s_add_u32 s16, s20, 0x200000
	s_addc_u32 s17, s21, 0
	s_add_i32 s41, s41, s28
	v_lshl_add_u64 v[142:143], s[16:17], 0, v[0:1]
	s_mov_b32 m0, s41
	s_nop 0
	global_load_lds_dwordx4 v[142:143], off
	v_lshl_add_u64 v[142:143], s[16:17], 0, v[130:131]
	s_add_i32 m0, s41, 0x2000
	s_nop 0
	global_load_lds_dwordx4 v[142:143], off
	s_waitcnt vmcnt(6)
	s_barrier
	s_setprio 1
	v_mfma_f32_16x16x32_bf16 v[54:57], v[190:193], v[158:161], v[54:57]
	v_mfma_f32_16x16x32_bf16 v[50:53], v[198:201], v[158:161], v[50:53]
	v_mfma_f32_16x16x32_bf16 v[38:41], v[190:193], v[166:169], v[38:41]
	v_mfma_f32_16x16x32_bf16 v[34:37], v[198:201], v[166:169], v[34:37]
	v_mfma_f32_16x16x32_bf16 v[22:25], v[190:193], v[174:177], v[22:25]
	v_mfma_f32_16x16x32_bf16 v[18:21], v[198:201], v[174:177], v[18:21]
	v_mfma_f32_16x16x32_bf16 v[6:9], v[190:193], v[182:185], v[6:9]
	v_mfma_f32_16x16x32_bf16 v[2:5], v[198:201], v[182:185], v[2:5]
	v_mfma_f32_16x16x32_bf16 v[54:57], v[194:197], v[162:165], v[54:57]
	v_mfma_f32_16x16x32_bf16 v[50:53], v[202:205], v[162:165], v[50:53]
	v_mfma_f32_16x16x32_bf16 v[38:41], v[194:197], v[170:173], v[38:41]
	v_mfma_f32_16x16x32_bf16 v[34:37], v[202:205], v[170:173], v[34:37]
	v_mfma_f32_16x16x32_bf16 v[22:25], v[194:197], v[178:181], v[22:25]
	v_mfma_f32_16x16x32_bf16 v[18:21], v[202:205], v[178:181], v[18:21]
	v_mfma_f32_16x16x32_bf16 v[6:9], v[194:197], v[186:189], v[6:9]
	v_mfma_f32_16x16x32_bf16 v[2:5], v[202:205], v[186:189], v[2:5]
	s_setprio 0
	s_add_i32 s41, 0, 0x18000
	v_add_u32_e32 v154, s41, v139
	s_barrier
	ds_read_b128 v[142:145], v154
	ds_read_b128 v[146:149], v154 offset:1024
	ds_read_b128 v[150:153], v154 offset:2048
	ds_read_b128 v[154:157], v154 offset:3072
	s_add_u32 s16, s22, 0x200000
	s_addc_u32 s17, s23, 0
	s_mov_b32 m0, s29
	v_lshl_add_u64 v[190:191], s[16:17], 0, v[0:1]
	ds_read_b128 v[158:161], v141 offset:32768
	ds_read_b128 v[162:165], v141 offset:33792
	ds_read_b128 v[166:169], v141 offset:34816
	ds_read_b128 v[170:173], v141 offset:35840
	ds_read_b128 v[174:177], v141 offset:36864
	ds_read_b128 v[178:181], v141 offset:37888
	ds_read_b128 v[182:185], v141 offset:38912
	ds_read_b128 v[186:189], v141 offset:39936
	global_load_lds_dwordx4 v[190:191], off
	v_lshl_add_u64 v[190:191], s[16:17], 0, v[130:131]
	s_mov_b32 m0, s30
	s_nop 0
	global_load_lds_dwordx4 v[190:191], off
	s_waitcnt lgkmcnt(8)
	s_barrier
	s_waitcnt lgkmcnt(0)
	s_setprio 1
	s_waitcnt lgkmcnt(0)
	v_mfma_f32_16x16x32_bf16 v[126:129], v[142:145], v[158:161], v[126:129]
	v_mfma_f32_16x16x32_bf16 v[122:125], v[150:153], v[158:161], v[122:125]
	v_mfma_f32_16x16x32_bf16 v[110:113], v[142:145], v[166:169], v[110:113]
	v_mfma_f32_16x16x32_bf16 v[106:109], v[150:153], v[166:169], v[106:109]
	v_mfma_f32_16x16x32_bf16 v[94:97], v[142:145], v[174:177], v[94:97]
	v_mfma_f32_16x16x32_bf16 v[90:93], v[150:153], v[174:177], v[90:93]
	v_mfma_f32_16x16x32_bf16 v[78:81], v[142:145], v[182:185], v[78:81]
	v_mfma_f32_16x16x32_bf16 v[74:77], v[150:153], v[182:185], v[74:77]
	v_mfma_f32_16x16x32_bf16 v[126:129], v[146:149], v[162:165], v[126:129]
	v_mfma_f32_16x16x32_bf16 v[122:125], v[154:157], v[162:165], v[122:125]
	v_mfma_f32_16x16x32_bf16 v[110:113], v[146:149], v[170:173], v[110:113]
	v_mfma_f32_16x16x32_bf16 v[106:109], v[154:157], v[170:173], v[106:109]
	v_mfma_f32_16x16x32_bf16 v[94:97], v[146:149], v[178:181], v[94:97]
	v_mfma_f32_16x16x32_bf16 v[90:93], v[154:157], v[178:181], v[90:93]
	v_mfma_f32_16x16x32_bf16 v[78:81], v[146:149], v[186:189], v[78:81]
	v_mfma_f32_16x16x32_bf16 v[74:77], v[154:157], v[186:189], v[74:77]
	s_setprio 0
	s_barrier
	s_add_i32 s22, 0, 0x1c000
	s_add_i32 s16, s41, s28
	v_add_u32_e32 v202, s22, v139
	v_lshl_add_u64 v[136:137], v[136:137], 0, s[44:45]
	s_mov_b32 m0, s16
	ds_read_b128 v[190:193], v202
	ds_read_b128 v[194:197], v202 offset:1024
	ds_read_b128 v[198:201], v202 offset:2048
	ds_read_b128 v[202:205], v202 offset:3072
	global_load_lds_dwordx4 v[136:137], off
	v_lshl_add_u64 v[136:137], v[206:207], 0, s[44:45]
	s_add_i32 m0, s16, 0x2000
	s_nop 0
	global_load_lds_dwordx4 v[136:137], off
	s_barrier
	s_waitcnt lgkmcnt(0)
	s_setprio 1
	s_waitcnt lgkmcnt(0)
	v_mfma_f32_16x16x32_bf16 v[118:121], v[190:193], v[158:161], v[118:121]
	v_mfma_f32_16x16x32_bf16 v[114:117], v[198:201], v[158:161], v[114:117]
	v_mfma_f32_16x16x32_bf16 v[102:105], v[190:193], v[166:169], v[102:105]
	v_mfma_f32_16x16x32_bf16 v[98:101], v[198:201], v[166:169], v[98:101]
	v_mfma_f32_16x16x32_bf16 v[86:89], v[190:193], v[174:177], v[86:89]
	v_mfma_f32_16x16x32_bf16 v[82:85], v[198:201], v[174:177], v[82:85]
	v_mfma_f32_16x16x32_bf16 v[70:73], v[190:193], v[182:185], v[70:73]
	v_mfma_f32_16x16x32_bf16 v[66:69], v[198:201], v[182:185], v[66:69]
	v_mfma_f32_16x16x32_bf16 v[118:121], v[194:197], v[162:165], v[118:121]
	v_mfma_f32_16x16x32_bf16 v[114:117], v[202:205], v[162:165], v[114:117]
	v_mfma_f32_16x16x32_bf16 v[102:105], v[194:197], v[170:173], v[102:105]
	v_mfma_f32_16x16x32_bf16 v[98:101], v[202:205], v[170:173], v[98:101]
	v_mfma_f32_16x16x32_bf16 v[86:89], v[194:197], v[178:181], v[86:89]
	v_mfma_f32_16x16x32_bf16 v[82:85], v[202:205], v[178:181], v[82:85]
	v_mfma_f32_16x16x32_bf16 v[70:73], v[194:197], v[186:189], v[70:73]
	v_mfma_f32_16x16x32_bf16 v[66:69], v[202:205], v[186:189], v[66:69]
	s_setprio 0
	s_mov_b32 m0, s34
	v_lshl_add_u64 v[136:137], v[208:209], 0, s[44:45]
	s_barrier
	ds_read_b128 v[158:161], v141 offset:49152
	ds_read_b128 v[162:165], v141 offset:50176
	ds_read_b128 v[166:169], v141 offset:51200
	ds_read_b128 v[170:173], v141 offset:52224
	ds_read_b128 v[174:177], v141 offset:53248
	ds_read_b128 v[178:181], v141 offset:54272
	ds_read_b128 v[182:185], v141 offset:55296
	ds_read_b128 v[186:189], v141 offset:56320
	global_load_lds_dwordx4 v[136:137], off
	v_lshl_add_u64 v[136:137], v[210:211], 0, s[44:45]
	s_mov_b32 m0, s35
	s_nop 0
	global_load_lds_dwordx4 v[136:137], off
	s_barrier
; #define PG8_STAGE(bufoff, gbase, voff) do { _Pragma("unroll") for (int _i = 0; _i < 2; ++_i) \
;         __builtin_amdgcn_global_load_lds((const unsigned*)((const char*)(gbase) + (voff)[_i]), (LAS unsigned*)(lds + (bufoff) + ldsw + _i * 8192), 16, 0, 0); } while (0)
; #define PG8_MMA(ai, bj, At, Bt) do { __builtin_amdgcn_s_setprio(1); _Pragma("unroll") for (int m = 0; m < 4; ++m) _Pragma("unroll") for (int n = 0; n < 2; ++n) _Pragma("unroll") for (int k = 0; k < 2; ++k) \
;         acc[ai][bj][m][n] = __builtin_amdgcn_mfma_f32_16x16x32_bf16(Bt[n][k], At[m][k], acc[ai][bj][m][n], 0, 0, 0); __builtin_amdgcn_s_setprio(0); } while (0)
; #define PG8_WAIT_V(n) asm volatile("s_waitcnt vmcnt(" #n ")" ::: "memory")
; #define PG8_WAIT_L(n) asm volatile("s_waitcnt lgkmcnt(" #n ")" ::: "memory")
; template <class Epi, class Sched>
; __device__ __forceinline__ void gemm_phase(LAS unsigned char* lds, const Gemm g, const Sched& S, const Epi& E) {
;     ...
;             PG8_BAR; PG8_WAIT_L(0); PG8_MMA(1, 0, At, B0); PG8_BAR; PG8_SCHED;
;             PG8_STAGE(PG8_SB(1, 1), b3 + hstep, voffB);
;             PG8_WAIT_V(6); PG8_BAR; PG8_MMA(1, 1, At, B1); PG8_BAR;
;         }
;         E(acc, cur, wr, wc, fr, fq); S.done(cur);
;         if (!has_next) break;
;     __device__ __forceinline__ void operator()(const f32x4 (&acc)[2][2][4][2], const pg8::Unit& u, int wr, int wc, int fr, int fq) const {
;         const int row0 = u.pm * 256 + wr * 64 + fr; const int col0 = u.pn * 256 + wc * 32 + 4 * fq;
; #pragma unroll
;         for (int ai = 0; ai < 2; ++ai)
; #pragma unroll
;             for (int m = 0; m < 4; ++m) { const int row = row0 + ai * 128 + m * 16;
;                 const float* ip; float* op; int b;
;                 if (row < ML_ROWS) { b = row >> 11; ip = xi + (size_t)row * D; op = xo + (size_t)row * D; }
;                 else { b = 8; ip = ci + (size_t)(row - ML_ROWS) * D; op = co + (size_t)(row - ML_ROWS) * D; }
;                 const float* gp = mod + (size_t)b * 12288 + slot * 2048;
; #pragma unroll
;                 for (int bj = 0; bj < 2; ++bj)
; #pragma unroll
;                     for (int n = 0; n < 2; ++n) { const int c = col0 + bj * 128 + n * 16;
;                         const f32x4 r = *(const f32x4*)(ip + c), g = *(const f32x4*)(gp + c);
;                         *(f32x4*)(op + c) = r + g * acc[ai][bj][m][n]; } }
	s_waitcnt lgkmcnt(0)
	s_setprio 1
	s_waitcnt lgkmcnt(0)
	v_mfma_f32_16x16x32_bf16 v[62:65], v[142:145], v[158:161], v[62:65]
	v_mfma_f32_16x16x32_bf16 v[58:61], v[150:153], v[158:161], v[58:61]
	v_mfma_f32_16x16x32_bf16 v[46:49], v[142:145], v[166:169], v[46:49]
	v_mfma_f32_16x16x32_bf16 v[42:45], v[150:153], v[166:169], v[42:45]
	v_mfma_f32_16x16x32_bf16 v[30:33], v[142:145], v[174:177], v[30:33]
	v_mfma_f32_16x16x32_bf16 v[26:29], v[150:153], v[174:177], v[26:29]
	v_mfma_f32_16x16x32_bf16 v[14:17], v[142:145], v[182:185], v[14:17]
	v_mfma_f32_16x16x32_bf16 v[10:13], v[150:153], v[182:185], v[10:13]
	v_mfma_f32_16x16x32_bf16 v[62:65], v[146:149], v[162:165], v[62:65]
	v_mfma_f32_16x16x32_bf16 v[58:61], v[154:157], v[162:165], v[58:61]
	v_mfma_f32_16x16x32_bf16 v[46:49], v[146:149], v[170:173], v[46:49]
	v_mfma_f32_16x16x32_bf16 v[42:45], v[154:157], v[170:173], v[42:45]
	v_mfma_f32_16x16x32_bf16 v[30:33], v[146:149], v[178:181], v[30:33]
	v_mfma_f32_16x16x32_bf16 v[26:29], v[154:157], v[178:181], v[26:29]
	v_mfma_f32_16x16x32_bf16 v[14:17], v[146:149], v[186:189], v[14:17]
	v_mfma_f32_16x16x32_bf16 v[10:13], v[154:157], v[186:189], v[10:13]
	s_setprio 0
	s_barrier
	s_add_u32 s16, s20, 0x200080
	s_addc_u32 s17, s21, 0
	s_add_i32 s20, s22, s28
	v_lshl_add_u64 v[136:137], s[16:17], 0, v[0:1]
	s_mov_b32 m0, s20
	s_nop 0
	global_load_lds_dwordx4 v[136:137], off
	v_lshl_add_u64 v[136:137], s[16:17], 0, v[130:131]
	s_add_i32 m0, s20, 0x2000
	s_nop 0
	global_load_lds_dwordx4 v[136:137], off
	s_waitcnt vmcnt(6)
	s_barrier
	s_setprio 1
	v_mfma_f32_16x16x32_bf16 v[54:57], v[190:193], v[158:161], v[54:57]
	v_mfma_f32_16x16x32_bf16 v[50:53], v[198:201], v[158:161], v[50:53]
	v_mfma_f32_16x16x32_bf16 v[38:41], v[190:193], v[166:169], v[38:41]
	v_mfma_f32_16x16x32_bf16 v[34:37], v[198:201], v[166:169], v[34:37]
	v_mfma_f32_16x16x32_bf16 v[22:25], v[190:193], v[174:177], v[22:25]
	v_mfma_f32_16x16x32_bf16 v[18:21], v[198:201], v[174:177], v[18:21]
	v_mfma_f32_16x16x32_bf16 v[6:9], v[190:193], v[182:185], v[6:9]
	v_mfma_f32_16x16x32_bf16 v[2:5], v[198:201], v[182:185], v[2:5]
	v_mfma_f32_16x16x32_bf16 v[54:57], v[194:197], v[162:165], v[54:57]
	v_mfma_f32_16x16x32_bf16 v[50:53], v[202:205], v[162:165], v[50:53]
	v_mfma_f32_16x16x32_bf16 v[38:41], v[194:197], v[170:173], v[38:41]
	v_mfma_f32_16x16x32_bf16 v[34:37], v[202:205], v[170:173], v[34:37]
	v_mfma_f32_16x16x32_bf16 v[22:25], v[194:197], v[178:181], v[22:25]
	v_mfma_f32_16x16x32_bf16 v[18:21], v[202:205], v[178:181], v[18:21]
	v_mfma_f32_16x16x32_bf16 v[6:9], v[194:197], v[186:189], v[6:9]
	v_mfma_f32_16x16x32_bf16 v[2:5], v[202:205], v[186:189], v[2:5]
	s_setprio 0
	s_add_i32 s40, s40, 2
	s_add_u32 s38, s38, 0x100
	s_addc_u32 s39, s39, 0
	s_cmpk_gt_u32 s40, 0x7d
	s_mov_b64 s[16:17], s[18:19]
	s_barrier
	s_cbranch_scc0 .LBB0_1343
	s_lshl_b32 s3, s14, 8
	s_add_i32 s3, s3, s31
	v_readlane_b32 s40, v251, 0
	v_readlane_b32 s41, v251, 1
	v_readlane_b32 s42, v251, 2
	v_readlane_b32 s43, v251, 3
	v_readlane_b32 s44, v251, 4
	v_readlane_b32 s45, v251, 5
	v_readlane_b32 s46, v251, 6
	v_readlane_b32 s47, v251, 7
	v_readlane_b32 s18, v254, 2
	v_readlane_b32 s19, v254, 3
	s_add_i32 s5, s3, 0xffffc000
	s_ashr_i32 s7, s3, 11
	s_cmpk_lt_i32 s3, 0x4000
	s_cselect_b32 s20, s42, s60
	s_cselect_b32 s21, s43, s61
	s_cselect_b32 s5, s3, s5
	s_cselect_b32 s7, s7, 8
	s_mul_i32 s7, s7, 0xc000
	s_add_u32 s18, s18, s7
	s_addc_u32 s19, s19, 0
	s_add_u32 s18, s18, 0xa000
	s_addc_u32 s19, s19, 0
	v_add_u32_e32 v136, s5, v138
	v_lshl_or_b32 v137, s12, 8, v140
	v_lshlrev_b32_e32 v137, 2, v137
	v_lshl_or_b32 v136, v136, 13, v137
	s_mov_b32 s12, s4
	s_mov_b32 s14, s6
	s_cmp_lg_u32 s36, 3
	s_cbranch_scc1 .Lsk_normal
	v_readlane_b32 s5, v253, 24
	s_cmpk_lg_u32 s46, 0x100
	s_cbranch_scc1 .Lsk_normal
	s_cmpk_lg_u32 s5, 0x240
	s_cbranch_scc0 .Lsk_epi
.Lsk_normal:
	v_add_u32_e32 v142, 0x20000, v136
	v_add_u32_e32 v143, 0x40000, v136
	v_add_u32_e32 v144, 0x60000, v136
	v_add_u32_e32 v145, 0x100000, v136
	v_add_u32_e32 v210, 0x120000, v136
	v_add_u32_e32 v211, 0x140000, v136
	global_load_dwordx4 v[146:149], v137, s[18:19]
	global_load_dwordx4 v[150:153], v137, s[18:19] offset:64
	global_load_dwordx4 v[154:157], v137, s[18:19] offset:512
	global_load_dwordx4 v[158:161], v137, s[18:19] offset:576
	v_add_u32_e32 v137, 0x160000, v136
	global_load_dwordx4 v[162:165], v136, s[20:21]
	global_load_dwordx4 v[166:169], v136, s[20:21] offset:64
	global_load_dwordx4 v[170:173], v136, s[20:21] offset:512
	global_load_dwordx4 v[174:177], v136, s[20:21] offset:576
	global_load_dwordx4 v[178:181], v142, s[20:21]
	global_load_dwordx4 v[182:185], v142, s[20:21] offset:64
	global_load_dwordx4 v[186:189], v142, s[20:21] offset:512
	global_load_dwordx4 v[190:193], v142, s[20:21] offset:576
	global_load_dwordx4 v[194:197], v143, s[20:21]
	global_load_dwordx4 v[198:201], v143, s[20:21] offset:64
	global_load_dwordx4 v[202:205], v143, s[20:21] offset:512
	global_load_dwordx4 v[206:209], v143, s[20:21] offset:576
	s_waitcnt vmcnt(8)
	v_pk_fma_f32 v[126:127], v[126:127], v[146:147], v[162:163]
	v_pk_fma_f32 v[128:129], v[128:129], v[148:149], v[164:165]
	v_pk_fma_f32 v[122:123], v[122:123], v[150:151], v[166:167]
	v_pk_fma_f32 v[124:125], v[124:125], v[152:153], v[168:169]
	v_pk_fma_f32 v[118:119], v[118:119], v[154:155], v[170:171]
	v_pk_fma_f32 v[120:121], v[120:121], v[156:157], v[172:173]
	v_pk_fma_f32 v[114:115], v[114:115], v[158:159], v[174:175]
	v_pk_fma_f32 v[116:117], v[116:117], v[160:161], v[176:177]
	global_store_dwordx4 v136, v[126:129], s[20:21]
	global_store_dwordx4 v136, v[122:125], s[20:21] offset:64
	global_store_dwordx4 v136, v[118:121], s[20:21] offset:512
	global_store_dwordx4 v136, v[114:117], s[20:21] offset:576
	global_load_dwordx4 v[162:165], v144, s[20:21]
	global_load_dwordx4 v[166:169], v144, s[20:21] offset:64
	global_load_dwordx4 v[170:173], v144, s[20:21] offset:512
	global_load_dwordx4 v[174:177], v144, s[20:21] offset:576
	s_waitcnt vmcnt(12)
;     __device__ __forceinline__ void operator()(const f32x4 (&acc)[2][2][4][2], const pg8::Unit& u, int wr, int wc, int fr, int fq) const {
;     ...
;                 for (int bj = 0; bj < 2; ++bj)
; #pragma unroll
;                     for (int n = 0; n < 2; ++n) { const int c = col0 + bj * 128 + n * 16;
;                         const f32x4 r = *(const f32x4*)(ip + c), g = *(const f32x4*)(gp + c);
;                         *(f32x4*)(op + c) = r + g * acc[ai][bj][m][n]; } }
	v_pk_fma_f32 v[110:111], v[110:111], v[146:147], v[178:179]
	v_pk_fma_f32 v[112:113], v[112:113], v[148:149], v[180:181]
	v_pk_fma_f32 v[106:107], v[106:107], v[150:151], v[182:183]
	v_pk_fma_f32 v[108:109], v[108:109], v[152:153], v[184:185]
	v_pk_fma_f32 v[102:103], v[102:103], v[154:155], v[186:187]
	v_pk_fma_f32 v[104:105], v[104:105], v[156:157], v[188:189]
	v_pk_fma_f32 v[98:99], v[98:99], v[158:159], v[190:191]
	v_pk_fma_f32 v[100:101], v[100:101], v[160:161], v[192:193]
	global_store_dwordx4 v142, v[110:113], s[20:21]
	global_store_dwordx4 v142, v[106:109], s[20:21] offset:64
	global_store_dwordx4 v142, v[102:105], s[20:21] offset:512
	global_store_dwordx4 v142, v[98:101], s[20:21] offset:576
	global_load_dwordx4 v[178:181], v145, s[20:21]
	global_load_dwordx4 v[182:185], v145, s[20:21] offset:64
	global_load_dwordx4 v[186:189], v145, s[20:21] offset:512
	global_load_dwordx4 v[190:193], v145, s[20:21] offset:576
	s_waitcnt vmcnt(16)
	v_pk_fma_f32 v[94:95], v[94:95], v[146:147], v[194:195]
	v_pk_fma_f32 v[96:97], v[96:97], v[148:149], v[196:197]
	v_pk_fma_f32 v[90:91], v[90:91], v[150:151], v[198:199]
	v_pk_fma_f32 v[92:93], v[92:93], v[152:153], v[200:201]
	v_pk_fma_f32 v[86:87], v[86:87], v[154:155], v[202:203]
	v_pk_fma_f32 v[88:89], v[88:89], v[156:157], v[204:205]
	v_pk_fma_f32 v[82:83], v[82:83], v[158:159], v[206:207]
	v_pk_fma_f32 v[84:85], v[84:85], v[160:161], v[208:209]
	global_store_dwordx4 v143, v[94:97], s[20:21]
	global_store_dwordx4 v143, v[90:93], s[20:21] offset:64
	global_store_dwordx4 v143, v[86:89], s[20:21] offset:512
	global_store_dwordx4 v143, v[82:85], s[20:21] offset:576
	global_load_dwordx4 v[194:197], v210, s[20:21]
	global_load_dwordx4 v[198:201], v210, s[20:21] offset:64
	global_load_dwordx4 v[202:205], v210, s[20:21] offset:512
	global_load_dwordx4 v[206:209], v210, s[20:21] offset:576
	s_waitcnt vmcnt(16)
	v_pk_fma_f32 v[78:79], v[78:79], v[146:147], v[162:163]
	v_pk_fma_f32 v[80:81], v[80:81], v[148:149], v[164:165]
	v_pk_fma_f32 v[74:75], v[74:75], v[150:151], v[166:167]
	v_pk_fma_f32 v[76:77], v[76:77], v[152:153], v[168:169]
	v_pk_fma_f32 v[70:71], v[70:71], v[154:155], v[170:171]
	v_pk_fma_f32 v[72:73], v[72:73], v[156:157], v[172:173]
	v_pk_fma_f32 v[66:67], v[66:67], v[158:159], v[174:175]
	v_pk_fma_f32 v[68:69], v[68:69], v[160:161], v[176:177]
	global_store_dwordx4 v144, v[78:81], s[20:21]
	global_store_dwordx4 v144, v[74:77], s[20:21] offset:64
	global_store_dwordx4 v144, v[70:73], s[20:21] offset:512
	global_store_dwordx4 v144, v[66:69], s[20:21] offset:576
	global_load_dwordx4 v[162:165], v211, s[20:21]
	global_load_dwordx4 v[166:169], v211, s[20:21] offset:64
	global_load_dwordx4 v[170:173], v211, s[20:21] offset:512
	global_load_dwordx4 v[174:177], v211, s[20:21] offset:576
	s_waitcnt vmcnt(16)
	v_pk_fma_f32 v[62:63], v[62:63], v[146:147], v[178:179]
	v_pk_fma_f32 v[64:65], v[64:65], v[148:149], v[180:181]
	v_pk_fma_f32 v[58:59], v[58:59], v[150:151], v[182:183]
	v_pk_fma_f32 v[60:61], v[60:61], v[152:153], v[184:185]
	v_pk_fma_f32 v[54:55], v[54:55], v[154:155], v[186:187]
	v_pk_fma_f32 v[56:57], v[56:57], v[156:157], v[188:189]
	v_pk_fma_f32 v[50:51], v[50:51], v[158:159], v[190:191]
	v_pk_fma_f32 v[52:53], v[52:53], v[160:161], v[192:193]
	global_store_dwordx4 v145, v[62:65], s[20:21]
	global_store_dwordx4 v145, v[58:61], s[20:21] offset:64
	global_store_dwordx4 v145, v[54:57], s[20:21] offset:512
	global_store_dwordx4 v145, v[50:53], s[20:21] offset:576
	global_load_dwordx4 v[178:181], v137, s[20:21]
	global_load_dwordx4 v[182:185], v137, s[20:21] offset:64
	global_load_dwordx4 v[186:189], v137, s[20:21] offset:512
	global_load_dwordx4 v[190:193], v137, s[20:21] offset:576
	s_waitcnt vmcnt(16)
	v_pk_fma_f32 v[46:47], v[46:47], v[146:147], v[194:195]
	v_pk_fma_f32 v[48:49], v[48:49], v[148:149], v[196:197]
	v_pk_fma_f32 v[42:43], v[42:43], v[150:151], v[198:199]
	v_pk_fma_f32 v[44:45], v[44:45], v[152:153], v[200:201]
	v_pk_fma_f32 v[38:39], v[38:39], v[154:155], v[202:203]
	v_pk_fma_f32 v[40:41], v[40:41], v[156:157], v[204:205]
	v_pk_fma_f32 v[34:35], v[34:35], v[158:159], v[206:207]
	v_pk_fma_f32 v[36:37], v[36:37], v[160:161], v[208:209]
	global_store_dwordx4 v210, v[46:49], s[20:21]
	global_store_dwordx4 v210, v[42:45], s[20:21] offset:64
	global_store_dwordx4 v210, v[38:41], s[20:21] offset:512
	global_store_dwordx4 v210, v[34:37], s[20:21] offset:576
	s_waitcnt vmcnt(12)
	v_pk_fma_f32 v[30:31], v[30:31], v[146:147], v[162:163]
	v_pk_fma_f32 v[32:33], v[32:33], v[148:149], v[164:165]
	v_pk_fma_f32 v[26:27], v[26:27], v[150:151], v[166:167]
	v_pk_fma_f32 v[28:29], v[28:29], v[152:153], v[168:169]
	v_pk_fma_f32 v[22:23], v[22:23], v[154:155], v[170:171]
	v_pk_fma_f32 v[24:25], v[24:25], v[156:157], v[172:173]
	v_pk_fma_f32 v[18:19], v[18:19], v[158:159], v[174:175]
	v_pk_fma_f32 v[20:21], v[20:21], v[160:161], v[176:177]
	global_store_dwordx4 v211, v[30:33], s[20:21]
	global_store_dwordx4 v211, v[26:29], s[20:21] offset:64
	global_store_dwordx4 v211, v[22:25], s[20:21] offset:512
	global_store_dwordx4 v211, v[18:21], s[20:21] offset:576
	s_waitcnt vmcnt(8)
	v_pk_fma_f32 v[14:15], v[14:15], v[146:147], v[178:179]
	v_pk_fma_f32 v[16:17], v[16:17], v[148:149], v[180:181]
	v_pk_fma_f32 v[10:11], v[10:11], v[150:151], v[182:183]
	v_pk_fma_f32 v[12:13], v[12:13], v[152:153], v[184:185]
	v_pk_fma_f32 v[6:7], v[6:7], v[154:155], v[186:187]
	v_pk_fma_f32 v[8:9], v[8:9], v[156:157], v[188:189]
	v_pk_fma_f32 v[2:3], v[2:3], v[158:159], v[190:191]
	v_pk_fma_f32 v[4:5], v[4:5], v[160:161], v[192:193]
	global_store_dwordx4 v137, v[14:17], s[20:21]
	global_store_dwordx4 v137, v[10:13], s[20:21] offset:64
	global_store_dwordx4 v137, v[6:9], s[20:21] offset:512
	global_store_dwordx4 v137, v[2:5], s[20:21] offset:576
; template <class Epi, class Sched>
; __device__ __forceinline__ void gemm_phase(LAS unsigned char* lds, const Gemm g, const Sched& S, const Epi& E) {
;     ...
;         E(acc, cur, wr, wc, fr, fq); S.done(cur);
;         if (!has_next) break;
;     __device__ __forceinline__ void operator()(const f32x4 (&acc)[2][2][4][2], const pg8::Unit& u, int wr, int wc, int fr, int fq) const {
;     ...
;                 for (int bj = 0; bj < 2; ++bj)
; #pragma unroll
;                     for (int n = 0; n < 2; ++n) { const int c = col0 + bj * 128 + n * 16;
;                         const f32x4 r = *(const f32x4*)(ip + c), g = *(const f32x4*)(gp + c);
;                         *(f32x4*)(op + c) = r + g * acc[ai][bj][m][n]; } }
.Lsk_post:
	s_mov_b64 s[18:19], s[10:11]
	s_mov_b64 s[16:17], s[8:9]
	s_and_b64 vcc, exec, s[0:1]
	s_cbranch_vccz .LBB0_1340
	s_branch .Lsk_exit
.Lsk_epi:
	global_load_dwordx4 v[146:149], v137, s[18:19]
	global_load_dwordx4 v[150:153], v137, s[18:19] offset:64
	global_load_dwordx4 v[154:157], v137, s[18:19] offset:512
	global_load_dwordx4 v[158:161], v137, s[18:19] offset:576
	v_and_b32_e32 v142, 3, v138
	v_mul_u32_u24_e32 v142, 0x1ffc, v142
	v_sub_u32_e32 v136, v136, v142
	v_add_u32_e32 v210, 0x2000, v136
	v_add_u32_e32 v211, 0x4000, v136
	v_add_u32_e32 v137, 0x6000, v136
	s_mov_b64 s[16:17], vcc
	s_waitcnt vmcnt(0)
	v_pk_mul_f32 v[126:127], v[126:127], v[146:147]
	v_pk_mul_f32 v[128:129], v[128:129], v[148:149]
	v_pk_mul_f32 v[122:123], v[122:123], v[150:151]
	v_pk_mul_f32 v[124:125], v[124:125], v[152:153]
	v_pk_mul_f32 v[118:119], v[118:119], v[154:155]
	v_pk_mul_f32 v[120:121], v[120:121], v[156:157]
	v_pk_mul_f32 v[114:115], v[114:115], v[158:159]
	v_pk_mul_f32 v[116:117], v[116:117], v[160:161]
	v_pk_mul_f32 v[110:111], v[110:111], v[146:147]
	v_pk_mul_f32 v[112:113], v[112:113], v[148:149]
	v_pk_mul_f32 v[106:107], v[106:107], v[150:151]
	v_pk_mul_f32 v[108:109], v[108:109], v[152:153]
	v_pk_mul_f32 v[102:103], v[102:103], v[154:155]
	v_pk_mul_f32 v[104:105], v[104:105], v[156:157]
	v_pk_mul_f32 v[98:99], v[98:99], v[158:159]
	v_pk_mul_f32 v[100:101], v[100:101], v[160:161]
	v_pk_mul_f32 v[94:95], v[94:95], v[146:147]
	v_pk_mul_f32 v[96:97], v[96:97], v[148:149]
	v_pk_mul_f32 v[90:91], v[90:91], v[150:151]
	v_pk_mul_f32 v[92:93], v[92:93], v[152:153]
	v_pk_mul_f32 v[86:87], v[86:87], v[154:155]
	v_pk_mul_f32 v[88:89], v[88:89], v[156:157]
	v_pk_mul_f32 v[82:83], v[82:83], v[158:159]
	v_pk_mul_f32 v[84:85], v[84:85], v[160:161]
	v_pk_mul_f32 v[78:79], v[78:79], v[146:147]
	v_pk_mul_f32 v[80:81], v[80:81], v[148:149]
	v_pk_mul_f32 v[74:75], v[74:75], v[150:151]
	v_pk_mul_f32 v[76:77], v[76:77], v[152:153]
	v_pk_mul_f32 v[70:71], v[70:71], v[154:155]
	v_pk_mul_f32 v[72:73], v[72:73], v[156:157]
	v_pk_mul_f32 v[66:67], v[66:67], v[158:159]
	v_pk_mul_f32 v[68:69], v[68:69], v[160:161]
	v_pk_mul_f32 v[62:63], v[62:63], v[146:147]
	v_pk_mul_f32 v[64:65], v[64:65], v[148:149]
	v_pk_mul_f32 v[58:59], v[58:59], v[150:151]
	v_pk_mul_f32 v[60:61], v[60:61], v[152:153]
	v_pk_mul_f32 v[54:55], v[54:55], v[154:155]
	v_pk_mul_f32 v[56:57], v[56:57], v[156:157]
	v_pk_mul_f32 v[50:51], v[50:51], v[158:159]
	v_pk_mul_f32 v[52:53], v[52:53], v[160:161]
	v_pk_mul_f32 v[46:47], v[46:47], v[146:147]
	v_pk_mul_f32 v[48:49], v[48:49], v[148:149]
	v_pk_mul_f32 v[42:43], v[42:43], v[150:151]
	v_pk_mul_f32 v[44:45], v[44:45], v[152:153]
	v_pk_mul_f32 v[38:39], v[38:39], v[154:155]
	v_pk_mul_f32 v[40:41], v[40:41], v[156:157]
	v_pk_mul_f32 v[34:35], v[34:35], v[158:159]
	v_pk_mul_f32 v[36:37], v[36:37], v[160:161]
	v_pk_mul_f32 v[30:31], v[30:31], v[146:147]
	v_pk_mul_f32 v[32:33], v[32:33], v[148:149]
	v_pk_mul_f32 v[26:27], v[26:27], v[150:151]
	v_pk_mul_f32 v[28:29], v[28:29], v[152:153]
	v_pk_mul_f32 v[22:23], v[22:23], v[154:155]
	v_pk_mul_f32 v[24:25], v[24:25], v[156:157]
	v_pk_mul_f32 v[18:19], v[18:19], v[158:159]
	v_pk_mul_f32 v[20:21], v[20:21], v[160:161]
	v_pk_mul_f32 v[14:15], v[14:15], v[146:147]
	v_pk_mul_f32 v[16:17], v[16:17], v[148:149]
	v_pk_mul_f32 v[10:11], v[10:11], v[150:151]
	v_pk_mul_f32 v[12:13], v[12:13], v[152:153]
	v_pk_mul_f32 v[6:7], v[6:7], v[154:155]
	v_pk_mul_f32 v[8:9], v[8:9], v[156:157]
	v_pk_mul_f32 v[2:3], v[2:3], v[158:159]
	v_pk_mul_f32 v[4:5], v[4:5], v[160:161]
	s_mov_b32 vcc_lo, 0x55555555
	s_mov_b32 vcc_hi, 0x55555555
	v_cndmask_b32_dpp v162, v127, v126, vcc quad_perm:[1,0,3,2] row_mask:0xf bank_mask:0xf
	v_cndmask_b32_dpp v164, v129, v128, vcc quad_perm:[1,0,3,2] row_mask:0xf bank_mask:0xf
	v_cndmask_b32_dpp v166, v123, v122, vcc quad_perm:[1,0,3,2] row_mask:0xf bank_mask:0xf
	v_cndmask_b32_dpp v168, v125, v124, vcc quad_perm:[1,0,3,2] row_mask:0xf bank_mask:0xf
	v_cndmask_b32_dpp v170, v119, v118, vcc quad_perm:[1,0,3,2] row_mask:0xf bank_mask:0xf
	v_cndmask_b32_dpp v172, v121, v120, vcc quad_perm:[1,0,3,2] row_mask:0xf bank_mask:0xf
	v_cndmask_b32_dpp v174, v115, v114, vcc quad_perm:[1,0,3,2] row_mask:0xf bank_mask:0xf
	v_cndmask_b32_dpp v176, v117, v116, vcc quad_perm:[1,0,3,2] row_mask:0xf bank_mask:0xf
	s_mov_b32 vcc_lo, 0xaaaaaaaa
	s_mov_b32 vcc_hi, 0xaaaaaaaa
	v_cndmask_b32_dpp v163, v126, v127, vcc quad_perm:[1,0,3,2] row_mask:0xf bank_mask:0xf
	v_cndmask_b32_dpp v165, v128, v129, vcc quad_perm:[1,0,3,2] row_mask:0xf bank_mask:0xf
	v_cndmask_b32_dpp v167, v122, v123, vcc quad_perm:[1,0,3,2] row_mask:0xf bank_mask:0xf
	v_cndmask_b32_dpp v169, v124, v125, vcc quad_perm:[1,0,3,2] row_mask:0xf bank_mask:0xf
	v_cndmask_b32_dpp v171, v118, v119, vcc quad_perm:[1,0,3,2] row_mask:0xf bank_mask:0xf
	v_cndmask_b32_dpp v173, v120, v121, vcc quad_perm:[1,0,3,2] row_mask:0xf bank_mask:0xf
	v_cndmask_b32_dpp v175, v114, v115, vcc quad_perm:[1,0,3,2] row_mask:0xf bank_mask:0xf
	v_cndmask_b32_dpp v177, v116, v117, vcc quad_perm:[1,0,3,2] row_mask:0xf bank_mask:0xf
	s_mov_b32 vcc_lo, 0x33333333
	s_mov_b32 vcc_hi, 0x33333333
	v_cndmask_b32_dpp v126, v164, v162, vcc quad_perm:[2,3,0,1] row_mask:0xf bank_mask:0xf
	v_cndmask_b32_dpp v127, v165, v163, vcc quad_perm:[2,3,0,1] row_mask:0xf bank_mask:0xf
	v_cndmask_b32_dpp v122, v168, v166, vcc quad_perm:[2,3,0,1] row_mask:0xf bank_mask:0xf
	v_cndmask_b32_dpp v123, v169, v167, vcc quad_perm:[2,3,0,1] row_mask:0xf bank_mask:0xf
	v_cndmask_b32_dpp v118, v172, v170, vcc quad_perm:[2,3,0,1] row_mask:0xf bank_mask:0xf
	v_cndmask_b32_dpp v119, v173, v171, vcc quad_perm:[2,3,0,1] row_mask:0xf bank_mask:0xf
;     __device__ __forceinline__ void operator()(const f32x4 (&acc)[2][2][4][2], const pg8::Unit& u, int wr, int wc, int fr, int fq) const {
;     ...
;                 for (int bj = 0; bj < 2; ++bj)
; #pragma unroll
;                     for (int n = 0; n < 2; ++n) { const int c = col0 + bj * 128 + n * 16;
;                         const f32x4 r = *(const f32x4*)(ip + c), g = *(const f32x4*)(gp + c);
;                         *(f32x4*)(op + c) = r + g * acc[ai][bj][m][n]; } }
	v_cndmask_b32_dpp v114, v176, v174, vcc quad_perm:[2,3,0,1] row_mask:0xf bank_mask:0xf
	v_cndmask_b32_dpp v115, v177, v175, vcc quad_perm:[2,3,0,1] row_mask:0xf bank_mask:0xf
	s_mov_b32 vcc_lo, 0xcccccccc
	s_mov_b32 vcc_hi, 0xcccccccc
	v_cndmask_b32_dpp v128, v162, v164, vcc quad_perm:[2,3,0,1] row_mask:0xf bank_mask:0xf
	v_cndmask_b32_dpp v129, v163, v165, vcc quad_perm:[2,3,0,1] row_mask:0xf bank_mask:0xf
	v_cndmask_b32_dpp v124, v166, v168, vcc quad_perm:[2,3,0,1] row_mask:0xf bank_mask:0xf
	v_cndmask_b32_dpp v125, v167, v169, vcc quad_perm:[2,3,0,1] row_mask:0xf bank_mask:0xf
	v_cndmask_b32_dpp v120, v170, v172, vcc quad_perm:[2,3,0,1] row_mask:0xf bank_mask:0xf
	v_cndmask_b32_dpp v121, v171, v173, vcc quad_perm:[2,3,0,1] row_mask:0xf bank_mask:0xf
	v_cndmask_b32_dpp v116, v174, v176, vcc quad_perm:[2,3,0,1] row_mask:0xf bank_mask:0xf
	v_cndmask_b32_dpp v117, v175, v177, vcc quad_perm:[2,3,0,1] row_mask:0xf bank_mask:0xf
	v_add_u32_e32 v142, 0x0, v136
	v_add_u32_e32 v143, 0x0, v210
	v_add_u32_e32 v144, 0x0, v211
	v_add_u32_e32 v145, 0x0, v137
	s_nop 0
	global_atomic_add_f32 v142, v126, s[20:21] offset:0
	global_atomic_add_f32 v143, v127, s[20:21] offset:0
	global_atomic_add_f32 v144, v128, s[20:21] offset:0
	global_atomic_add_f32 v145, v129, s[20:21] offset:0
	global_atomic_add_f32 v142, v122, s[20:21] offset:64
	global_atomic_add_f32 v143, v123, s[20:21] offset:64
	global_atomic_add_f32 v144, v124, s[20:21] offset:64
	global_atomic_add_f32 v145, v125, s[20:21] offset:64
	global_atomic_add_f32 v142, v118, s[20:21] offset:512
	global_atomic_add_f32 v143, v119, s[20:21] offset:512
	global_atomic_add_f32 v144, v120, s[20:21] offset:512
	global_atomic_add_f32 v145, v121, s[20:21] offset:512
	global_atomic_add_f32 v142, v114, s[20:21] offset:576
	global_atomic_add_f32 v143, v115, s[20:21] offset:576
	global_atomic_add_f32 v144, v116, s[20:21] offset:576
	global_atomic_add_f32 v145, v117, s[20:21] offset:576
	s_mov_b32 vcc_lo, 0x55555555
	s_mov_b32 vcc_hi, 0x55555555
	v_cndmask_b32_dpp v178, v111, v110, vcc quad_perm:[1,0,3,2] row_mask:0xf bank_mask:0xf
	v_cndmask_b32_dpp v180, v113, v112, vcc quad_perm:[1,0,3,2] row_mask:0xf bank_mask:0xf
	v_cndmask_b32_dpp v182, v107, v106, vcc quad_perm:[1,0,3,2] row_mask:0xf bank_mask:0xf
	v_cndmask_b32_dpp v184, v109, v108, vcc quad_perm:[1,0,3,2] row_mask:0xf bank_mask:0xf
	v_cndmask_b32_dpp v186, v103, v102, vcc quad_perm:[1,0,3,2] row_mask:0xf bank_mask:0xf
	v_cndmask_b32_dpp v188, v105, v104, vcc quad_perm:[1,0,3,2] row_mask:0xf bank_mask:0xf
	v_cndmask_b32_dpp v190, v99, v98, vcc quad_perm:[1,0,3,2] row_mask:0xf bank_mask:0xf
	v_cndmask_b32_dpp v192, v101, v100, vcc quad_perm:[1,0,3,2] row_mask:0xf bank_mask:0xf
	s_mov_b32 vcc_lo, 0xaaaaaaaa
	s_mov_b32 vcc_hi, 0xaaaaaaaa
	v_cndmask_b32_dpp v179, v110, v111, vcc quad_perm:[1,0,3,2] row_mask:0xf bank_mask:0xf
	v_cndmask_b32_dpp v181, v112, v113, vcc quad_perm:[1,0,3,2] row_mask:0xf bank_mask:0xf
	v_cndmask_b32_dpp v183, v106, v107, vcc quad_perm:[1,0,3,2] row_mask:0xf bank_mask:0xf
	v_cndmask_b32_dpp v185, v108, v109, vcc quad_perm:[1,0,3,2] row_mask:0xf bank_mask:0xf
	v_cndmask_b32_dpp v187, v102, v103, vcc quad_perm:[1,0,3,2] row_mask:0xf bank_mask:0xf
	v_cndmask_b32_dpp v189, v104, v105, vcc quad_perm:[1,0,3,2] row_mask:0xf bank_mask:0xf
	v_cndmask_b32_dpp v191, v98, v99, vcc quad_perm:[1,0,3,2] row_mask:0xf bank_mask:0xf
	v_cndmask_b32_dpp v193, v100, v101, vcc quad_perm:[1,0,3,2] row_mask:0xf bank_mask:0xf
	s_mov_b32 vcc_lo, 0x33333333
	s_mov_b32 vcc_hi, 0x33333333
	v_cndmask_b32_dpp v110, v180, v178, vcc quad_perm:[2,3,0,1] row_mask:0xf bank_mask:0xf
	v_cndmask_b32_dpp v111, v181, v179, vcc quad_perm:[2,3,0,1] row_mask:0xf bank_mask:0xf
	v_cndmask_b32_dpp v106, v184, v182, vcc quad_perm:[2,3,0,1] row_mask:0xf bank_mask:0xf
	v_cndmask_b32_dpp v107, v185, v183, vcc quad_perm:[2,3,0,1] row_mask:0xf bank_mask:0xf
	v_cndmask_b32_dpp v102, v188, v186, vcc quad_perm:[2,3,0,1] row_mask:0xf bank_mask:0xf
	v_cndmask_b32_dpp v103, v189, v187, vcc quad_perm:[2,3,0,1] row_mask:0xf bank_mask:0xf
	v_cndmask_b32_dpp v98, v192, v190, vcc quad_perm:[2,3,0,1] row_mask:0xf bank_mask:0xf
	v_cndmask_b32_dpp v99, v193, v191, vcc quad_perm:[2,3,0,1] row_mask:0xf bank_mask:0xf
	s_mov_b32 vcc_lo, 0xcccccccc
	s_mov_b32 vcc_hi, 0xcccccccc
	v_cndmask_b32_dpp v112, v178, v180, vcc quad_perm:[2,3,0,1] row_mask:0xf bank_mask:0xf
	v_cndmask_b32_dpp v113, v179, v181, vcc quad_perm:[2,3,0,1] row_mask:0xf bank_mask:0xf
	v_cndmask_b32_dpp v108, v182, v184, vcc quad_perm:[2,3,0,1] row_mask:0xf bank_mask:0xf
	v_cndmask_b32_dpp v109, v183, v185, vcc quad_perm:[2,3,0,1] row_mask:0xf bank_mask:0xf
	v_cndmask_b32_dpp v104, v186, v188, vcc quad_perm:[2,3,0,1] row_mask:0xf bank_mask:0xf
	v_cndmask_b32_dpp v105, v187, v189, vcc quad_perm:[2,3,0,1] row_mask:0xf bank_mask:0xf
	v_cndmask_b32_dpp v100, v190, v192, vcc quad_perm:[2,3,0,1] row_mask:0xf bank_mask:0xf
	v_cndmask_b32_dpp v101, v191, v193, vcc quad_perm:[2,3,0,1] row_mask:0xf bank_mask:0xf
	v_add_u32_e32 v142, 0x20000, v136
	v_add_u32_e32 v143, 0x20000, v210
	v_add_u32_e32 v144, 0x20000, v211
	v_add_u32_e32 v145, 0x20000, v137
	s_nop 0
	global_atomic_add_f32 v142, v110, s[20:21] offset:0
	global_atomic_add_f32 v143, v111, s[20:21] offset:0
	global_atomic_add_f32 v144, v112, s[20:21] offset:0
	global_atomic_add_f32 v145, v113, s[20:21] offset:0
	global_atomic_add_f32 v142, v106, s[20:21] offset:64
	global_atomic_add_f32 v143, v107, s[20:21] offset:64
	global_atomic_add_f32 v144, v108, s[20:21] offset:64
	global_atomic_add_f32 v145, v109, s[20:21] offset:64
	global_atomic_add_f32 v142, v102, s[20:21] offset:512
;     __device__ __forceinline__ void operator()(const f32x4 (&acc)[2][2][4][2], const pg8::Unit& u, int wr, int wc, int fr, int fq) const {
;     ...
;                 for (int bj = 0; bj < 2; ++bj)
; #pragma unroll
;                     for (int n = 0; n < 2; ++n) { const int c = col0 + bj * 128 + n * 16;
;                         const f32x4 r = *(const f32x4*)(ip + c), g = *(const f32x4*)(gp + c);
;                         *(f32x4*)(op + c) = r + g * acc[ai][bj][m][n]; } }
	global_atomic_add_f32 v143, v103, s[20:21] offset:512
	global_atomic_add_f32 v144, v104, s[20:21] offset:512
	global_atomic_add_f32 v145, v105, s[20:21] offset:512
	global_atomic_add_f32 v142, v98, s[20:21] offset:576
	global_atomic_add_f32 v143, v99, s[20:21] offset:576
	global_atomic_add_f32 v144, v100, s[20:21] offset:576
	global_atomic_add_f32 v145, v101, s[20:21] offset:576
	s_mov_b32 vcc_lo, 0x55555555
	s_mov_b32 vcc_hi, 0x55555555
	v_cndmask_b32_dpp v162, v95, v94, vcc quad_perm:[1,0,3,2] row_mask:0xf bank_mask:0xf
	v_cndmask_b32_dpp v164, v97, v96, vcc quad_perm:[1,0,3,2] row_mask:0xf bank_mask:0xf
	v_cndmask_b32_dpp v166, v91, v90, vcc quad_perm:[1,0,3,2] row_mask:0xf bank_mask:0xf
	v_cndmask_b32_dpp v168, v93, v92, vcc quad_perm:[1,0,3,2] row_mask:0xf bank_mask:0xf
	v_cndmask_b32_dpp v170, v87, v86, vcc quad_perm:[1,0,3,2] row_mask:0xf bank_mask:0xf
	v_cndmask_b32_dpp v172, v89, v88, vcc quad_perm:[1,0,3,2] row_mask:0xf bank_mask:0xf
	v_cndmask_b32_dpp v174, v83, v82, vcc quad_perm:[1,0,3,2] row_mask:0xf bank_mask:0xf
	v_cndmask_b32_dpp v176, v85, v84, vcc quad_perm:[1,0,3,2] row_mask:0xf bank_mask:0xf
	s_mov_b32 vcc_lo, 0xaaaaaaaa
	s_mov_b32 vcc_hi, 0xaaaaaaaa
	v_cndmask_b32_dpp v163, v94, v95, vcc quad_perm:[1,0,3,2] row_mask:0xf bank_mask:0xf
	v_cndmask_b32_dpp v165, v96, v97, vcc quad_perm:[1,0,3,2] row_mask:0xf bank_mask:0xf
	v_cndmask_b32_dpp v167, v90, v91, vcc quad_perm:[1,0,3,2] row_mask:0xf bank_mask:0xf
	v_cndmask_b32_dpp v169, v92, v93, vcc quad_perm:[1,0,3,2] row_mask:0xf bank_mask:0xf
	v_cndmask_b32_dpp v171, v86, v87, vcc quad_perm:[1,0,3,2] row_mask:0xf bank_mask:0xf
	v_cndmask_b32_dpp v173, v88, v89, vcc quad_perm:[1,0,3,2] row_mask:0xf bank_mask:0xf
	v_cndmask_b32_dpp v175, v82, v83, vcc quad_perm:[1,0,3,2] row_mask:0xf bank_mask:0xf
	v_cndmask_b32_dpp v177, v84, v85, vcc quad_perm:[1,0,3,2] row_mask:0xf bank_mask:0xf
	s_mov_b32 vcc_lo, 0x33333333
	s_mov_b32 vcc_hi, 0x33333333
	v_cndmask_b32_dpp v94, v164, v162, vcc quad_perm:[2,3,0,1] row_mask:0xf bank_mask:0xf
	v_cndmask_b32_dpp v95, v165, v163, vcc quad_perm:[2,3,0,1] row_mask:0xf bank_mask:0xf
	v_cndmask_b32_dpp v90, v168, v166, vcc quad_perm:[2,3,0,1] row_mask:0xf bank_mask:0xf
	v_cndmask_b32_dpp v91, v169, v167, vcc quad_perm:[2,3,0,1] row_mask:0xf bank_mask:0xf
	v_cndmask_b32_dpp v86, v172, v170, vcc quad_perm:[2,3,0,1] row_mask:0xf bank_mask:0xf
	v_cndmask_b32_dpp v87, v173, v171, vcc quad_perm:[2,3,0,1] row_mask:0xf bank_mask:0xf
	v_cndmask_b32_dpp v82, v176, v174, vcc quad_perm:[2,3,0,1] row_mask:0xf bank_mask:0xf
	v_cndmask_b32_dpp v83, v177, v175, vcc quad_perm:[2,3,0,1] row_mask:0xf bank_mask:0xf
	s_mov_b32 vcc_lo, 0xcccccccc
	s_mov_b32 vcc_hi, 0xcccccccc
	v_cndmask_b32_dpp v96, v162, v164, vcc quad_perm:[2,3,0,1] row_mask:0xf bank_mask:0xf
	v_cndmask_b32_dpp v97, v163, v165, vcc quad_perm:[2,3,0,1] row_mask:0xf bank_mask:0xf
	v_cndmask_b32_dpp v92, v166, v168, vcc quad_perm:[2,3,0,1] row_mask:0xf bank_mask:0xf
	v_cndmask_b32_dpp v93, v167, v169, vcc quad_perm:[2,3,0,1] row_mask:0xf bank_mask:0xf
	v_cndmask_b32_dpp v88, v170, v172, vcc quad_perm:[2,3,0,1] row_mask:0xf bank_mask:0xf
	v_cndmask_b32_dpp v89, v171, v173, vcc quad_perm:[2,3,0,1] row_mask:0xf bank_mask:0xf
	v_cndmask_b32_dpp v84, v174, v176, vcc quad_perm:[2,3,0,1] row_mask:0xf bank_mask:0xf
	v_cndmask_b32_dpp v85, v175, v177, vcc quad_perm:[2,3,0,1] row_mask:0xf bank_mask:0xf
	v_add_u32_e32 v142, 0x40000, v136
	v_add_u32_e32 v143, 0x40000, v210
	v_add_u32_e32 v144, 0x40000, v211
	v_add_u32_e32 v145, 0x40000, v137
	s_nop 0
	global_atomic_add_f32 v142, v94, s[20:21] offset:0
	global_atomic_add_f32 v143, v95, s[20:21] offset:0
	global_atomic_add_f32 v144, v96, s[20:21] offset:0
	global_atomic_add_f32 v145, v97, s[20:21] offset:0
	global_atomic_add_f32 v142, v90, s[20:21] offset:64
	global_atomic_add_f32 v143, v91, s[20:21] offset:64
	global_atomic_add_f32 v144, v92, s[20:21] offset:64
	global_atomic_add_f32 v145, v93, s[20:21] offset:64
	global_atomic_add_f32 v142, v86, s[20:21] offset:512
	global_atomic_add_f32 v143, v87, s[20:21] offset:512
	global_atomic_add_f32 v144, v88, s[20:21] offset:512
	global_atomic_add_f32 v145, v89, s[20:21] offset:512
	global_atomic_add_f32 v142, v82, s[20:21] offset:576
	global_atomic_add_f32 v143, v83, s[20:21] offset:576
	global_atomic_add_f32 v144, v84, s[20:21] offset:576
	global_atomic_add_f32 v145, v85, s[20:21] offset:576
	s_mov_b32 vcc_lo, 0x55555555
	s_mov_b32 vcc_hi, 0x55555555
	v_cndmask_b32_dpp v178, v79, v78, vcc quad_perm:[1,0,3,2] row_mask:0xf bank_mask:0xf
	v_cndmask_b32_dpp v180, v81, v80, vcc quad_perm:[1,0,3,2] row_mask:0xf bank_mask:0xf
	v_cndmask_b32_dpp v182, v75, v74, vcc quad_perm:[1,0,3,2] row_mask:0xf bank_mask:0xf
	v_cndmask_b32_dpp v184, v77, v76, vcc quad_perm:[1,0,3,2] row_mask:0xf bank_mask:0xf
	v_cndmask_b32_dpp v186, v71, v70, vcc quad_perm:[1,0,3,2] row_mask:0xf bank_mask:0xf
	v_cndmask_b32_dpp v188, v73, v72, vcc quad_perm:[1,0,3,2] row_mask:0xf bank_mask:0xf
	v_cndmask_b32_dpp v190, v67, v66, vcc quad_perm:[1,0,3,2] row_mask:0xf bank_mask:0xf
	v_cndmask_b32_dpp v192, v69, v68, vcc quad_perm:[1,0,3,2] row_mask:0xf bank_mask:0xf
	s_mov_b32 vcc_lo, 0xaaaaaaaa
	s_mov_b32 vcc_hi, 0xaaaaaaaa
	v_cndmask_b32_dpp v179, v78, v79, vcc quad_perm:[1,0,3,2] row_mask:0xf bank_mask:0xf
	v_cndmask_b32_dpp v181, v80, v81, vcc quad_perm:[1,0,3,2] row_mask:0xf bank_mask:0xf
	v_cndmask_b32_dpp v183, v74, v75, vcc quad_perm:[1,0,3,2] row_mask:0xf bank_mask:0xf
	v_cndmask_b32_dpp v185, v76, v77, vcc quad_perm:[1,0,3,2] row_mask:0xf bank_mask:0xf
	v_cndmask_b32_dpp v187, v70, v71, vcc quad_perm:[1,0,3,2] row_mask:0xf bank_mask:0xf
;     __device__ __forceinline__ void operator()(const f32x4 (&acc)[2][2][4][2], const pg8::Unit& u, int wr, int wc, int fr, int fq) const {
;     ...
;                 for (int bj = 0; bj < 2; ++bj)
; #pragma unroll
;                     for (int n = 0; n < 2; ++n) { const int c = col0 + bj * 128 + n * 16;
;                         const f32x4 r = *(const f32x4*)(ip + c), g = *(const f32x4*)(gp + c);
;                         *(f32x4*)(op + c) = r + g * acc[ai][bj][m][n]; } }
	v_cndmask_b32_dpp v189, v72, v73, vcc quad_perm:[1,0,3,2] row_mask:0xf bank_mask:0xf
	v_cndmask_b32_dpp v191, v66, v67, vcc quad_perm:[1,0,3,2] row_mask:0xf bank_mask:0xf
	v_cndmask_b32_dpp v193, v68, v69, vcc quad_perm:[1,0,3,2] row_mask:0xf bank_mask:0xf
	s_mov_b32 vcc_lo, 0x33333333
	s_mov_b32 vcc_hi, 0x33333333
	v_cndmask_b32_dpp v78, v180, v178, vcc quad_perm:[2,3,0,1] row_mask:0xf bank_mask:0xf
	v_cndmask_b32_dpp v79, v181, v179, vcc quad_perm:[2,3,0,1] row_mask:0xf bank_mask:0xf
	v_cndmask_b32_dpp v74, v184, v182, vcc quad_perm:[2,3,0,1] row_mask:0xf bank_mask:0xf
	v_cndmask_b32_dpp v75, v185, v183, vcc quad_perm:[2,3,0,1] row_mask:0xf bank_mask:0xf
	v_cndmask_b32_dpp v70, v188, v186, vcc quad_perm:[2,3,0,1] row_mask:0xf bank_mask:0xf
	v_cndmask_b32_dpp v71, v189, v187, vcc quad_perm:[2,3,0,1] row_mask:0xf bank_mask:0xf
	v_cndmask_b32_dpp v66, v192, v190, vcc quad_perm:[2,3,0,1] row_mask:0xf bank_mask:0xf
	v_cndmask_b32_dpp v67, v193, v191, vcc quad_perm:[2,3,0,1] row_mask:0xf bank_mask:0xf
	s_mov_b32 vcc_lo, 0xcccccccc
	s_mov_b32 vcc_hi, 0xcccccccc
	v_cndmask_b32_dpp v80, v178, v180, vcc quad_perm:[2,3,0,1] row_mask:0xf bank_mask:0xf
	v_cndmask_b32_dpp v81, v179, v181, vcc quad_perm:[2,3,0,1] row_mask:0xf bank_mask:0xf
	v_cndmask_b32_dpp v76, v182, v184, vcc quad_perm:[2,3,0,1] row_mask:0xf bank_mask:0xf
	v_cndmask_b32_dpp v77, v183, v185, vcc quad_perm:[2,3,0,1] row_mask:0xf bank_mask:0xf
	v_cndmask_b32_dpp v72, v186, v188, vcc quad_perm:[2,3,0,1] row_mask:0xf bank_mask:0xf
	v_cndmask_b32_dpp v73, v187, v189, vcc quad_perm:[2,3,0,1] row_mask:0xf bank_mask:0xf
	v_cndmask_b32_dpp v68, v190, v192, vcc quad_perm:[2,3,0,1] row_mask:0xf bank_mask:0xf
	v_cndmask_b32_dpp v69, v191, v193, vcc quad_perm:[2,3,0,1] row_mask:0xf bank_mask:0xf
	v_add_u32_e32 v142, 0x60000, v136
	v_add_u32_e32 v143, 0x60000, v210
	v_add_u32_e32 v144, 0x60000, v211
	v_add_u32_e32 v145, 0x60000, v137
	s_nop 0
	global_atomic_add_f32 v142, v78, s[20:21] offset:0
	global_atomic_add_f32 v143, v79, s[20:21] offset:0
	global_atomic_add_f32 v144, v80, s[20:21] offset:0
	global_atomic_add_f32 v145, v81, s[20:21] offset:0
	global_atomic_add_f32 v142, v74, s[20:21] offset:64
	global_atomic_add_f32 v143, v75, s[20:21] offset:64
	global_atomic_add_f32 v144, v76, s[20:21] offset:64
	global_atomic_add_f32 v145, v77, s[20:21] offset:64
	global_atomic_add_f32 v142, v70, s[20:21] offset:512
	global_atomic_add_f32 v143, v71, s[20:21] offset:512
	global_atomic_add_f32 v144, v72, s[20:21] offset:512
	global_atomic_add_f32 v145, v73, s[20:21] offset:512
	global_atomic_add_f32 v142, v66, s[20:21] offset:576
	global_atomic_add_f32 v143, v67, s[20:21] offset:576
	global_atomic_add_f32 v144, v68, s[20:21] offset:576
	global_atomic_add_f32 v145, v69, s[20:21] offset:576
	s_mov_b32 vcc_lo, 0x55555555
	s_mov_b32 vcc_hi, 0x55555555
	v_cndmask_b32_dpp v162, v63, v62, vcc quad_perm:[1,0,3,2] row_mask:0xf bank_mask:0xf
	v_cndmask_b32_dpp v164, v65, v64, vcc quad_perm:[1,0,3,2] row_mask:0xf bank_mask:0xf
	v_cndmask_b32_dpp v166, v59, v58, vcc quad_perm:[1,0,3,2] row_mask:0xf bank_mask:0xf
	v_cndmask_b32_dpp v168, v61, v60, vcc quad_perm:[1,0,3,2] row_mask:0xf bank_mask:0xf
	v_cndmask_b32_dpp v170, v55, v54, vcc quad_perm:[1,0,3,2] row_mask:0xf bank_mask:0xf
	v_cndmask_b32_dpp v172, v57, v56, vcc quad_perm:[1,0,3,2] row_mask:0xf bank_mask:0xf
	v_cndmask_b32_dpp v174, v51, v50, vcc quad_perm:[1,0,3,2] row_mask:0xf bank_mask:0xf
	v_cndmask_b32_dpp v176, v53, v52, vcc quad_perm:[1,0,3,2] row_mask:0xf bank_mask:0xf
	s_mov_b32 vcc_lo, 0xaaaaaaaa
	s_mov_b32 vcc_hi, 0xaaaaaaaa
	v_cndmask_b32_dpp v163, v62, v63, vcc quad_perm:[1,0,3,2] row_mask:0xf bank_mask:0xf
	v_cndmask_b32_dpp v165, v64, v65, vcc quad_perm:[1,0,3,2] row_mask:0xf bank_mask:0xf
	v_cndmask_b32_dpp v167, v58, v59, vcc quad_perm:[1,0,3,2] row_mask:0xf bank_mask:0xf
	v_cndmask_b32_dpp v169, v60, v61, vcc quad_perm:[1,0,3,2] row_mask:0xf bank_mask:0xf
	v_cndmask_b32_dpp v171, v54, v55, vcc quad_perm:[1,0,3,2] row_mask:0xf bank_mask:0xf
	v_cndmask_b32_dpp v173, v56, v57, vcc quad_perm:[1,0,3,2] row_mask:0xf bank_mask:0xf
	v_cndmask_b32_dpp v175, v50, v51, vcc quad_perm:[1,0,3,2] row_mask:0xf bank_mask:0xf
	v_cndmask_b32_dpp v177, v52, v53, vcc quad_perm:[1,0,3,2] row_mask:0xf bank_mask:0xf
	s_mov_b32 vcc_lo, 0x33333333
	s_mov_b32 vcc_hi, 0x33333333
	v_cndmask_b32_dpp v62, v164, v162, vcc quad_perm:[2,3,0,1] row_mask:0xf bank_mask:0xf
	v_cndmask_b32_dpp v63, v165, v163, vcc quad_perm:[2,3,0,1] row_mask:0xf bank_mask:0xf
	v_cndmask_b32_dpp v58, v168, v166, vcc quad_perm:[2,3,0,1] row_mask:0xf bank_mask:0xf
	v_cndmask_b32_dpp v59, v169, v167, vcc quad_perm:[2,3,0,1] row_mask:0xf bank_mask:0xf
	v_cndmask_b32_dpp v54, v172, v170, vcc quad_perm:[2,3,0,1] row_mask:0xf bank_mask:0xf
	v_cndmask_b32_dpp v55, v173, v171, vcc quad_perm:[2,3,0,1] row_mask:0xf bank_mask:0xf
	v_cndmask_b32_dpp v50, v176, v174, vcc quad_perm:[2,3,0,1] row_mask:0xf bank_mask:0xf
	v_cndmask_b32_dpp v51, v177, v175, vcc quad_perm:[2,3,0,1] row_mask:0xf bank_mask:0xf
	s_mov_b32 vcc_lo, 0xcccccccc
	s_mov_b32 vcc_hi, 0xcccccccc
	v_cndmask_b32_dpp v64, v162, v164, vcc quad_perm:[2,3,0,1] row_mask:0xf bank_mask:0xf
	v_cndmask_b32_dpp v65, v163, v165, vcc quad_perm:[2,3,0,1] row_mask:0xf bank_mask:0xf
	v_cndmask_b32_dpp v60, v166, v168, vcc quad_perm:[2,3,0,1] row_mask:0xf bank_mask:0xf
	v_cndmask_b32_dpp v61, v167, v169, vcc quad_perm:[2,3,0,1] row_mask:0xf bank_mask:0xf
	v_cndmask_b32_dpp v56, v170, v172, vcc quad_perm:[2,3,0,1] row_mask:0xf bank_mask:0xf
	v_cndmask_b32_dpp v57, v171, v173, vcc quad_perm:[2,3,0,1] row_mask:0xf bank_mask:0xf
;     __device__ __forceinline__ void operator()(const f32x4 (&acc)[2][2][4][2], const pg8::Unit& u, int wr, int wc, int fr, int fq) const {
;         const int row0 = u.pm * 256 + wr * 64 + fr; const int col0 = u.pn * 256 + wc * 32 + 4 * fq;
; #pragma unroll
;         for (int ai = 0; ai < 2; ++ai)
; #pragma unroll
;             for (int m = 0; m < 4; ++m) { const int row = row0 + ai * 128 + m * 16;
;                 const float* ip; float* op; int b;
;                 if (row < ML_ROWS) { b = row >> 11; ip = xi + (size_t)row * D; op = xo + (size_t)row * D; }
;                 else { b = 8; ip = ci + (size_t)(row - ML_ROWS) * D; op = co + (size_t)(row - ML_ROWS) * D; }
;                 const float* gp = mod + (size_t)b * 12288 + slot * 2048;
; #pragma unroll
;                 for (int bj = 0; bj < 2; ++bj)
; #pragma unroll
;                     for (int n = 0; n < 2; ++n) { const int c = col0 + bj * 128 + n * 16;
;                         const f32x4 r = *(const f32x4*)(ip + c), g = *(const f32x4*)(gp + c);
;                         *(f32x4*)(op + c) = r + g * acc[ai][bj][m][n]; } }
	v_cndmask_b32_dpp v52, v174, v176, vcc quad_perm:[2,3,0,1] row_mask:0xf bank_mask:0xf
	v_cndmask_b32_dpp v53, v175, v177, vcc quad_perm:[2,3,0,1] row_mask:0xf bank_mask:0xf
	v_add_u32_e32 v142, 0x100000, v136
	v_add_u32_e32 v143, 0x100000, v210
	v_add_u32_e32 v144, 0x100000, v211
	v_add_u32_e32 v145, 0x100000, v137
	s_nop 0
	global_atomic_add_f32 v142, v62, s[20:21] offset:0
	global_atomic_add_f32 v143, v63, s[20:21] offset:0
	global_atomic_add_f32 v144, v64, s[20:21] offset:0
	global_atomic_add_f32 v145, v65, s[20:21] offset:0
	global_atomic_add_f32 v142, v58, s[20:21] offset:64
	global_atomic_add_f32 v143, v59, s[20:21] offset:64
	global_atomic_add_f32 v144, v60, s[20:21] offset:64
	global_atomic_add_f32 v145, v61, s[20:21] offset:64
	global_atomic_add_f32 v142, v54, s[20:21] offset:512
	global_atomic_add_f32 v143, v55, s[20:21] offset:512
	global_atomic_add_f32 v144, v56, s[20:21] offset:512
	global_atomic_add_f32 v145, v57, s[20:21] offset:512
	global_atomic_add_f32 v142, v50, s[20:21] offset:576
	global_atomic_add_f32 v143, v51, s[20:21] offset:576
	global_atomic_add_f32 v144, v52, s[20:21] offset:576
	global_atomic_add_f32 v145, v53, s[20:21] offset:576
	s_mov_b32 vcc_lo, 0x55555555
	s_mov_b32 vcc_hi, 0x55555555
	v_cndmask_b32_dpp v178, v47, v46, vcc quad_perm:[1,0,3,2] row_mask:0xf bank_mask:0xf
	v_cndmask_b32_dpp v180, v49, v48, vcc quad_perm:[1,0,3,2] row_mask:0xf bank_mask:0xf
	v_cndmask_b32_dpp v182, v43, v42, vcc quad_perm:[1,0,3,2] row_mask:0xf bank_mask:0xf
	v_cndmask_b32_dpp v184, v45, v44, vcc quad_perm:[1,0,3,2] row_mask:0xf bank_mask:0xf
	v_cndmask_b32_dpp v186, v39, v38, vcc quad_perm:[1,0,3,2] row_mask:0xf bank_mask:0xf
	v_cndmask_b32_dpp v188, v41, v40, vcc quad_perm:[1,0,3,2] row_mask:0xf bank_mask:0xf
	v_cndmask_b32_dpp v190, v35, v34, vcc quad_perm:[1,0,3,2] row_mask:0xf bank_mask:0xf
	v_cndmask_b32_dpp v192, v37, v36, vcc quad_perm:[1,0,3,2] row_mask:0xf bank_mask:0xf
	s_mov_b32 vcc_lo, 0xaaaaaaaa
	s_mov_b32 vcc_hi, 0xaaaaaaaa
	v_cndmask_b32_dpp v179, v46, v47, vcc quad_perm:[1,0,3,2] row_mask:0xf bank_mask:0xf
	v_cndmask_b32_dpp v181, v48, v49, vcc quad_perm:[1,0,3,2] row_mask:0xf bank_mask:0xf
	v_cndmask_b32_dpp v183, v42, v43, vcc quad_perm:[1,0,3,2] row_mask:0xf bank_mask:0xf
	v_cndmask_b32_dpp v185, v44, v45, vcc quad_perm:[1,0,3,2] row_mask:0xf bank_mask:0xf
	v_cndmask_b32_dpp v187, v38, v39, vcc quad_perm:[1,0,3,2] row_mask:0xf bank_mask:0xf
	v_cndmask_b32_dpp v189, v40, v41, vcc quad_perm:[1,0,3,2] row_mask:0xf bank_mask:0xf
	v_cndmask_b32_dpp v191, v34, v35, vcc quad_perm:[1,0,3,2] row_mask:0xf bank_mask:0xf
	v_cndmask_b32_dpp v193, v36, v37, vcc quad_perm:[1,0,3,2] row_mask:0xf bank_mask:0xf
	s_mov_b32 vcc_lo, 0x33333333
	s_mov_b32 vcc_hi, 0x33333333
	v_cndmask_b32_dpp v46, v180, v178, vcc quad_perm:[2,3,0,1] row_mask:0xf bank_mask:0xf
	v_cndmask_b32_dpp v47, v181, v179, vcc quad_perm:[2,3,0,1] row_mask:0xf bank_mask:0xf
	v_cndmask_b32_dpp v42, v184, v182, vcc quad_perm:[2,3,0,1] row_mask:0xf bank_mask:0xf
	v_cndmask_b32_dpp v43, v185, v183, vcc quad_perm:[2,3,0,1] row_mask:0xf bank_mask:0xf
	v_cndmask_b32_dpp v38, v188, v186, vcc quad_perm:[2,3,0,1] row_mask:0xf bank_mask:0xf
	v_cndmask_b32_dpp v39, v189, v187, vcc quad_perm:[2,3,0,1] row_mask:0xf bank_mask:0xf
	v_cndmask_b32_dpp v34, v192, v190, vcc quad_perm:[2,3,0,1] row_mask:0xf bank_mask:0xf
	v_cndmask_b32_dpp v35, v193, v191, vcc quad_perm:[2,3,0,1] row_mask:0xf bank_mask:0xf
	s_mov_b32 vcc_lo, 0xcccccccc
	s_mov_b32 vcc_hi, 0xcccccccc
	v_cndmask_b32_dpp v48, v178, v180, vcc quad_perm:[2,3,0,1] row_mask:0xf bank_mask:0xf
	v_cndmask_b32_dpp v49, v179, v181, vcc quad_perm:[2,3,0,1] row_mask:0xf bank_mask:0xf
	v_cndmask_b32_dpp v44, v182, v184, vcc quad_perm:[2,3,0,1] row_mask:0xf bank_mask:0xf
	v_cndmask_b32_dpp v45, v183, v185, vcc quad_perm:[2,3,0,1] row_mask:0xf bank_mask:0xf
	v_cndmask_b32_dpp v40, v186, v188, vcc quad_perm:[2,3,0,1] row_mask:0xf bank_mask:0xf
	v_cndmask_b32_dpp v41, v187, v189, vcc quad_perm:[2,3,0,1] row_mask:0xf bank_mask:0xf
	v_cndmask_b32_dpp v36, v190, v192, vcc quad_perm:[2,3,0,1] row_mask:0xf bank_mask:0xf
	v_cndmask_b32_dpp v37, v191, v193, vcc quad_perm:[2,3,0,1] row_mask:0xf bank_mask:0xf
	v_add_u32_e32 v142, 0x120000, v136
	v_add_u32_e32 v143, 0x120000, v210
	v_add_u32_e32 v144, 0x120000, v211
	v_add_u32_e32 v145, 0x120000, v137
	s_nop 0
	global_atomic_add_f32 v142, v46, s[20:21] offset:0
	global_atomic_add_f32 v143, v47, s[20:21] offset:0
	global_atomic_add_f32 v144, v48, s[20:21] offset:0
	global_atomic_add_f32 v145, v49, s[20:21] offset:0
	global_atomic_add_f32 v142, v42, s[20:21] offset:64
	global_atomic_add_f32 v143, v43, s[20:21] offset:64
	global_atomic_add_f32 v144, v44, s[20:21] offset:64
	global_atomic_add_f32 v145, v45, s[20:21] offset:64
	global_atomic_add_f32 v142, v38, s[20:21] offset:512
	global_atomic_add_f32 v143, v39, s[20:21] offset:512
	global_atomic_add_f32 v144, v40, s[20:21] offset:512
	global_atomic_add_f32 v145, v41, s[20:21] offset:512
	global_atomic_add_f32 v142, v34, s[20:21] offset:576
	global_atomic_add_f32 v143, v35, s[20:21] offset:576
	global_atomic_add_f32 v144, v36, s[20:21] offset:576
	global_atomic_add_f32 v145, v37, s[20:21] offset:576
	s_mov_b32 vcc_lo, 0x55555555
	s_mov_b32 vcc_hi, 0x55555555
	v_cndmask_b32_dpp v162, v31, v30, vcc quad_perm:[1,0,3,2] row_mask:0xf bank_mask:0xf
	v_cndmask_b32_dpp v164, v33, v32, vcc quad_perm:[1,0,3,2] row_mask:0xf bank_mask:0xf
	v_cndmask_b32_dpp v166, v27, v26, vcc quad_perm:[1,0,3,2] row_mask:0xf bank_mask:0xf
	v_cndmask_b32_dpp v168, v29, v28, vcc quad_perm:[1,0,3,2] row_mask:0xf bank_mask:0xf
	v_cndmask_b32_dpp v170, v23, v22, vcc quad_perm:[1,0,3,2] row_mask:0xf bank_mask:0xf
;     __device__ __forceinline__ void operator()(const f32x4 (&acc)[2][2][4][2], const pg8::Unit& u, int wr, int wc, int fr, int fq) const {
;         const int row0 = u.pm * 256 + wr * 64 + fr; const int col0 = u.pn * 256 + wc * 32 + 4 * fq;
; #pragma unroll
;         for (int ai = 0; ai < 2; ++ai)
; #pragma unroll
;             for (int m = 0; m < 4; ++m) { const int row = row0 + ai * 128 + m * 16;
;                 const float* ip; float* op; int b;
;                 if (row < ML_ROWS) { b = row >> 11; ip = xi + (size_t)row * D; op = xo + (size_t)row * D; }
;                 else { b = 8; ip = ci + (size_t)(row - ML_ROWS) * D; op = co + (size_t)(row - ML_ROWS) * D; }
;                 const float* gp = mod + (size_t)b * 12288 + slot * 2048;
; #pragma unroll
;                 for (int bj = 0; bj < 2; ++bj)
; #pragma unroll
;                     for (int n = 0; n < 2; ++n) { const int c = col0 + bj * 128 + n * 16;
;                         const f32x4 r = *(const f32x4*)(ip + c), g = *(const f32x4*)(gp + c);
;                         *(f32x4*)(op + c) = r + g * acc[ai][bj][m][n]; } }
	v_cndmask_b32_dpp v172, v25, v24, vcc quad_perm:[1,0,3,2] row_mask:0xf bank_mask:0xf
	v_cndmask_b32_dpp v174, v19, v18, vcc quad_perm:[1,0,3,2] row_mask:0xf bank_mask:0xf
	v_cndmask_b32_dpp v176, v21, v20, vcc quad_perm:[1,0,3,2] row_mask:0xf bank_mask:0xf
	s_mov_b32 vcc_lo, 0xaaaaaaaa
	s_mov_b32 vcc_hi, 0xaaaaaaaa
	v_cndmask_b32_dpp v163, v30, v31, vcc quad_perm:[1,0,3,2] row_mask:0xf bank_mask:0xf
	v_cndmask_b32_dpp v165, v32, v33, vcc quad_perm:[1,0,3,2] row_mask:0xf bank_mask:0xf
	v_cndmask_b32_dpp v167, v26, v27, vcc quad_perm:[1,0,3,2] row_mask:0xf bank_mask:0xf
	v_cndmask_b32_dpp v169, v28, v29, vcc quad_perm:[1,0,3,2] row_mask:0xf bank_mask:0xf
	v_cndmask_b32_dpp v171, v22, v23, vcc quad_perm:[1,0,3,2] row_mask:0xf bank_mask:0xf
	v_cndmask_b32_dpp v173, v24, v25, vcc quad_perm:[1,0,3,2] row_mask:0xf bank_mask:0xf
	v_cndmask_b32_dpp v175, v18, v19, vcc quad_perm:[1,0,3,2] row_mask:0xf bank_mask:0xf
	v_cndmask_b32_dpp v177, v20, v21, vcc quad_perm:[1,0,3,2] row_mask:0xf bank_mask:0xf
	s_mov_b32 vcc_lo, 0x33333333
	s_mov_b32 vcc_hi, 0x33333333
	v_cndmask_b32_dpp v30, v164, v162, vcc quad_perm:[2,3,0,1] row_mask:0xf bank_mask:0xf
	v_cndmask_b32_dpp v31, v165, v163, vcc quad_perm:[2,3,0,1] row_mask:0xf bank_mask:0xf
	v_cndmask_b32_dpp v26, v168, v166, vcc quad_perm:[2,3,0,1] row_mask:0xf bank_mask:0xf
	v_cndmask_b32_dpp v27, v169, v167, vcc quad_perm:[2,3,0,1] row_mask:0xf bank_mask:0xf
	v_cndmask_b32_dpp v22, v172, v170, vcc quad_perm:[2,3,0,1] row_mask:0xf bank_mask:0xf
	v_cndmask_b32_dpp v23, v173, v171, vcc quad_perm:[2,3,0,1] row_mask:0xf bank_mask:0xf
	v_cndmask_b32_dpp v18, v176, v174, vcc quad_perm:[2,3,0,1] row_mask:0xf bank_mask:0xf
	v_cndmask_b32_dpp v19, v177, v175, vcc quad_perm:[2,3,0,1] row_mask:0xf bank_mask:0xf
	s_mov_b32 vcc_lo, 0xcccccccc
	s_mov_b32 vcc_hi, 0xcccccccc
	v_cndmask_b32_dpp v32, v162, v164, vcc quad_perm:[2,3,0,1] row_mask:0xf bank_mask:0xf
	v_cndmask_b32_dpp v33, v163, v165, vcc quad_perm:[2,3,0,1] row_mask:0xf bank_mask:0xf
	v_cndmask_b32_dpp v28, v166, v168, vcc quad_perm:[2,3,0,1] row_mask:0xf bank_mask:0xf
	v_cndmask_b32_dpp v29, v167, v169, vcc quad_perm:[2,3,0,1] row_mask:0xf bank_mask:0xf
	v_cndmask_b32_dpp v24, v170, v172, vcc quad_perm:[2,3,0,1] row_mask:0xf bank_mask:0xf
	v_cndmask_b32_dpp v25, v171, v173, vcc quad_perm:[2,3,0,1] row_mask:0xf bank_mask:0xf
	v_cndmask_b32_dpp v20, v174, v176, vcc quad_perm:[2,3,0,1] row_mask:0xf bank_mask:0xf
	v_cndmask_b32_dpp v21, v175, v177, vcc quad_perm:[2,3,0,1] row_mask:0xf bank_mask:0xf
	v_add_u32_e32 v142, 0x140000, v136
	v_add_u32_e32 v143, 0x140000, v210
	v_add_u32_e32 v144, 0x140000, v211
	v_add_u32_e32 v145, 0x140000, v137
	s_nop 0
	global_atomic_add_f32 v142, v30, s[20:21] offset:0
	global_atomic_add_f32 v143, v31, s[20:21] offset:0
	global_atomic_add_f32 v144, v32, s[20:21] offset:0
	global_atomic_add_f32 v145, v33, s[20:21] offset:0
	global_atomic_add_f32 v142, v26, s[20:21] offset:64
	global_atomic_add_f32 v143, v27, s[20:21] offset:64
	global_atomic_add_f32 v144, v28, s[20:21] offset:64
	global_atomic_add_f32 v145, v29, s[20:21] offset:64
	global_atomic_add_f32 v142, v22, s[20:21] offset:512
	global_atomic_add_f32 v143, v23, s[20:21] offset:512
	global_atomic_add_f32 v144, v24, s[20:21] offset:512
	global_atomic_add_f32 v145, v25, s[20:21] offset:512
	global_atomic_add_f32 v142, v18, s[20:21] offset:576
	global_atomic_add_f32 v143, v19, s[20:21] offset:576
	global_atomic_add_f32 v144, v20, s[20:21] offset:576
	global_atomic_add_f32 v145, v21, s[20:21] offset:576
	s_mov_b32 vcc_lo, 0x55555555
	s_mov_b32 vcc_hi, 0x55555555
	v_cndmask_b32_dpp v178, v15, v14, vcc quad_perm:[1,0,3,2] row_mask:0xf bank_mask:0xf
	v_cndmask_b32_dpp v180, v17, v16, vcc quad_perm:[1,0,3,2] row_mask:0xf bank_mask:0xf
	v_cndmask_b32_dpp v182, v11, v10, vcc quad_perm:[1,0,3,2] row_mask:0xf bank_mask:0xf
; #define PG8_WAIT_V(n) asm volatile("s_waitcnt vmcnt(" #n ")" ::: "memory")
; #define PG8_BAR __builtin_amdgcn_s_barrier()
; template <class Epi, class Sched>
; __device__ __forceinline__ void gemm_phase(LAS unsigned char* lds, const Gemm g, const Sched& S, const Epi& E) {
;     ...
;     PG8_WAIT_V(0);
;     if (wr == 0) PG8_BAR;
;     __device__ __forceinline__ void operator()(const f32x4 (&acc)[2][2][4][2], const pg8::Unit& u, int wr, int wc, int fr, int fq) const {
;     ...
;             for (int m = 0; m < 4; ++m) { const int row = row0 + ai * 128 + m * 16;
;                 const float* ip; float* op; int b;
;                 if (row < ML_ROWS) { b = row >> 11; ip = xi + (size_t)row * D; op = xo + (size_t)row * D; }
;                 else { b = 8; ip = ci + (size_t)(row - ML_ROWS) * D; op = co + (size_t)(row - ML_ROWS) * D; }
;                 const float* gp = mod + (size_t)b * 12288 + slot * 2048;
; #pragma unroll
;                 for (int bj = 0; bj < 2; ++bj)
; #pragma unroll
;                     for (int n = 0; n < 2; ++n) { const int c = col0 + bj * 128 + n * 16;
;                         const f32x4 r = *(const f32x4*)(ip + c), g = *(const f32x4*)(gp + c);
;                         *(f32x4*)(op + c) = r + g * acc[ai][bj][m][n]; } }
	v_cndmask_b32_dpp v184, v13, v12, vcc quad_perm:[1,0,3,2] row_mask:0xf bank_mask:0xf
	v_cndmask_b32_dpp v186, v7, v6, vcc quad_perm:[1,0,3,2] row_mask:0xf bank_mask:0xf
	v_cndmask_b32_dpp v188, v9, v8, vcc quad_perm:[1,0,3,2] row_mask:0xf bank_mask:0xf
	v_cndmask_b32_dpp v190, v3, v2, vcc quad_perm:[1,0,3,2] row_mask:0xf bank_mask:0xf
	v_cndmask_b32_dpp v192, v5, v4, vcc quad_perm:[1,0,3,2] row_mask:0xf bank_mask:0xf
	s_mov_b32 vcc_lo, 0xaaaaaaaa
	s_mov_b32 vcc_hi, 0xaaaaaaaa
	v_cndmask_b32_dpp v179, v14, v15, vcc quad_perm:[1,0,3,2] row_mask:0xf bank_mask:0xf
	v_cndmask_b32_dpp v181, v16, v17, vcc quad_perm:[1,0,3,2] row_mask:0xf bank_mask:0xf
	v_cndmask_b32_dpp v183, v10, v11, vcc quad_perm:[1,0,3,2] row_mask:0xf bank_mask:0xf
	v_cndmask_b32_dpp v185, v12, v13, vcc quad_perm:[1,0,3,2] row_mask:0xf bank_mask:0xf
	v_cndmask_b32_dpp v187, v6, v7, vcc quad_perm:[1,0,3,2] row_mask:0xf bank_mask:0xf
	v_cndmask_b32_dpp v189, v8, v9, vcc quad_perm:[1,0,3,2] row_mask:0xf bank_mask:0xf
	v_cndmask_b32_dpp v191, v2, v3, vcc quad_perm:[1,0,3,2] row_mask:0xf bank_mask:0xf
	v_cndmask_b32_dpp v193, v4, v5, vcc quad_perm:[1,0,3,2] row_mask:0xf bank_mask:0xf
	s_mov_b32 vcc_lo, 0x33333333
	s_mov_b32 vcc_hi, 0x33333333
	v_cndmask_b32_dpp v14, v180, v178, vcc quad_perm:[2,3,0,1] row_mask:0xf bank_mask:0xf
	v_cndmask_b32_dpp v15, v181, v179, vcc quad_perm:[2,3,0,1] row_mask:0xf bank_mask:0xf
	v_cndmask_b32_dpp v10, v184, v182, vcc quad_perm:[2,3,0,1] row_mask:0xf bank_mask:0xf
	v_cndmask_b32_dpp v11, v185, v183, vcc quad_perm:[2,3,0,1] row_mask:0xf bank_mask:0xf
	v_cndmask_b32_dpp v6, v188, v186, vcc quad_perm:[2,3,0,1] row_mask:0xf bank_mask:0xf
	v_cndmask_b32_dpp v7, v189, v187, vcc quad_perm:[2,3,0,1] row_mask:0xf bank_mask:0xf
	v_cndmask_b32_dpp v2, v192, v190, vcc quad_perm:[2,3,0,1] row_mask:0xf bank_mask:0xf
	v_cndmask_b32_dpp v3, v193, v191, vcc quad_perm:[2,3,0,1] row_mask:0xf bank_mask:0xf
	s_mov_b32 vcc_lo, 0xcccccccc
	s_mov_b32 vcc_hi, 0xcccccccc
	v_cndmask_b32_dpp v16, v178, v180, vcc quad_perm:[2,3,0,1] row_mask:0xf bank_mask:0xf
	v_cndmask_b32_dpp v17, v179, v181, vcc quad_perm:[2,3,0,1] row_mask:0xf bank_mask:0xf
	v_cndmask_b32_dpp v12, v182, v184, vcc quad_perm:[2,3,0,1] row_mask:0xf bank_mask:0xf
	v_cndmask_b32_dpp v13, v183, v185, vcc quad_perm:[2,3,0,1] row_mask:0xf bank_mask:0xf
	v_cndmask_b32_dpp v8, v186, v188, vcc quad_perm:[2,3,0,1] row_mask:0xf bank_mask:0xf
	v_cndmask_b32_dpp v9, v187, v189, vcc quad_perm:[2,3,0,1] row_mask:0xf bank_mask:0xf
	v_cndmask_b32_dpp v4, v190, v192, vcc quad_perm:[2,3,0,1] row_mask:0xf bank_mask:0xf
	v_cndmask_b32_dpp v5, v191, v193, vcc quad_perm:[2,3,0,1] row_mask:0xf bank_mask:0xf
	v_add_u32_e32 v142, 0x160000, v136
	v_add_u32_e32 v143, 0x160000, v210
	v_add_u32_e32 v144, 0x160000, v211
	v_add_u32_e32 v145, 0x160000, v137
	s_nop 0
	global_atomic_add_f32 v142, v14, s[20:21] offset:0
	global_atomic_add_f32 v143, v15, s[20:21] offset:0
	global_atomic_add_f32 v144, v16, s[20:21] offset:0
	global_atomic_add_f32 v145, v17, s[20:21] offset:0
	global_atomic_add_f32 v142, v10, s[20:21] offset:64
	global_atomic_add_f32 v143, v11, s[20:21] offset:64
	global_atomic_add_f32 v144, v12, s[20:21] offset:64
	global_atomic_add_f32 v145, v13, s[20:21] offset:64
	global_atomic_add_f32 v142, v6, s[20:21] offset:512
	global_atomic_add_f32 v143, v7, s[20:21] offset:512
	global_atomic_add_f32 v144, v8, s[20:21] offset:512
	global_atomic_add_f32 v145, v9, s[20:21] offset:512
	global_atomic_add_f32 v142, v2, s[20:21] offset:576
	global_atomic_add_f32 v143, v3, s[20:21] offset:576
	global_atomic_add_f32 v144, v4, s[20:21] offset:576
	global_atomic_add_f32 v145, v5, s[20:21] offset:576
	s_mov_b64 vcc, s[16:17]
	s_branch .Lsk_post
.Lsk_exit:
	s_waitcnt vmcnt(0)
	s_cmpk_gt_u32 s24, 0xff
	s_cbranch_scc1 .LBB0_1347
	s_barrier
